# out/ffn2 GEMM residual epilogues hand-written like xo (up to 16 residual quads in flight, counted waits, statistics at the end)
# baseline (speedup 1.0000x reference)
.LBB0_110:
	v_readlane_b32 s4, v250, 25
	v_mbcnt_lo_u32_b32 v138, -1, 0
	v_mbcnt_hi_u32_b32 v138, -1, v138
	s_nop 1
	s_lshr_b32 s5, s4, 8
	s_bfe_u32 s4, s4, 0x20006
	v_and_b32_e32 v139, 15, v138
	v_lshrrev_b32_e32 v148, 4, v138
	s_lshl_b32 s70, s29, 8
	s_lshl_b32 s5, s5, 6
	s_add_u32 s5, s5, s70
	v_add_u32_e32 v139, s5, v139
	v_lshlrev_b32_e32 v149, 6, v139
	v_lshlrev_b32_e32 v150, 11, v139
	v_lshl_add_u32 v150, v148, 4, v150
	s_lshl_b32 s71, s4, 6
	v_add_u32_e32 v150, s71, v150
	v_mov_b32_e32 v151, v150
	s_lshl_b32 s76, s28, 9
	s_add_u32 s74, s30, s76
	s_addc_u32 s75, s31, 0
	s_lshl_b32 s57, s28, 2
	s_lshl_b32 s56, s28, 4
	s_lshl_b32 s76, s4, 2
	s_add_u32 s56, s56, s76
	v_readlane_b32 s28, v250, 26
	v_readlane_b32 s29, v250, 27
	global_load_dwordx4 v[184:187], v150, s[74:75]
	global_load_dwordx4 v[188:191], v150, s[74:75] offset:256
	v_add_u32_e32 v150, 0x8000, v150
	global_load_dwordx4 v[192:195], v150, s[74:75]
	global_load_dwordx4 v[196:199], v150, s[74:75] offset:256
	v_add_u32_e32 v150, 0x8000, v150
	global_load_dwordx4 v[200:203], v150, s[74:75]
	global_load_dwordx4 v[204:207], v150, s[74:75] offset:256
	v_add_u32_e32 v150, 0x8000, v150
	global_load_dwordx4 v[208:211], v150, s[74:75]
	global_load_dwordx4 v[212:215], v150, s[74:75] offset:256
	v_add_u32_e32 v150, 0x28000, v150
	global_load_dwordx4 v[216:219], v150, s[74:75]
	global_load_dwordx4 v[220:223], v150, s[74:75] offset:256
	v_add_u32_e32 v150, 0x8000, v150
	global_load_dwordx4 v[224:227], v150, s[74:75]
	global_load_dwordx4 v[228:231], v150, s[74:75] offset:256
	v_add_u32_e32 v150, 0x8000, v150
	global_load_dwordx4 v[232:235], v150, s[74:75]
	global_load_dwordx4 v[236:239], v150, s[74:75] offset:256
	v_add_u32_e32 v150, 0x8000, v150
	global_load_dwordx4 v[240:243], v150, s[74:75]
	global_load_dwordx4 v[244:247], v150, s[74:75] offset:256
	s_waitcnt vmcnt(15)
	v_lshlrev_b32_e32 v182, 16, v184
	v_and_b32_e32 v183, 0xffff0000, v184
	v_pk_add_f32 v[126:127], v[126:127], v[182:183]
	v_lshlrev_b32_e32 v248, 16, v185
	v_and_b32_e32 v249, 0xffff0000, v185
	v_pk_add_f32 v[128:129], v[128:129], v[248:249]
	v_lshlrev_b32_e32 v138, 16, v186
	v_and_b32_e32 v139, 0xffff0000, v186
	v_pk_add_f32 v[122:123], v[122:123], v[138:139]
	v_lshlrev_b32_e32 v182, 16, v187
	v_and_b32_e32 v183, 0xffff0000, v187
	v_pk_add_f32 v[124:125], v[124:125], v[182:183]
	v_cvt_pk_bf16_f32 v126, v126, v127
	v_cvt_pk_bf16_f32 v127, v128, v129
	v_cvt_pk_bf16_f32 v128, v122, v123
	v_cvt_pk_bf16_f32 v129, v124, v125
	global_store_dwordx4 v151, v[126:129], s[74:75]
	v_lshlrev_b32_e32 v184, 16, v126
	v_lshlrev_b32_e32 v185, 16, v127
	v_lshlrev_b32_e32 v186, 16, v128
	v_lshlrev_b32_e32 v187, 16, v129
	v_and_b32_e32 v122, 0xffff0000, v126
	v_and_b32_e32 v123, 0xffff0000, v127
	v_and_b32_e32 v124, 0xffff0000, v128
	v_and_b32_e32 v125, 0xffff0000, v129
	v_mul_f32_e32 v122, v122, v122
	v_mul_f32_e32 v123, v123, v123
	v_mul_f32_e32 v124, v124, v124
	v_mul_f32_e32 v125, v125, v125
	v_fmac_f32_e32 v122, v184, v184
	v_fmac_f32_e32 v123, v185, v185
	v_fmac_f32_e32 v124, v186, v186
	v_fmac_f32_e32 v125, v187, v187
	v_add_f32_e32 v122, v122, v123
	v_add_f32_e32 v122, v122, v124
	v_add_f32_e32 v122, v122, v125
	s_waitcnt vmcnt(15)
	v_lshlrev_b32_e32 v182, 16, v188
	v_and_b32_e32 v183, 0xffff0000, v188
	v_pk_add_f32 v[118:119], v[118:119], v[182:183]
	v_lshlrev_b32_e32 v248, 16, v189
	v_and_b32_e32 v249, 0xffff0000, v189
	v_pk_add_f32 v[120:121], v[120:121], v[248:249]
	v_lshlrev_b32_e32 v138, 16, v190
	v_and_b32_e32 v139, 0xffff0000, v190
	v_pk_add_f32 v[114:115], v[114:115], v[138:139]
	v_lshlrev_b32_e32 v182, 16, v191
	v_and_b32_e32 v183, 0xffff0000, v191
	v_pk_add_f32 v[116:117], v[116:117], v[182:183]
	v_cvt_pk_bf16_f32 v118, v118, v119
	v_cvt_pk_bf16_f32 v119, v120, v121
	v_cvt_pk_bf16_f32 v120, v114, v115
	v_cvt_pk_bf16_f32 v121, v116, v117
	global_store_dwordx4 v151, v[118:121], s[74:75] offset:256
	v_lshlrev_b32_e32 v188, 16, v118
	v_lshlrev_b32_e32 v189, 16, v119
	v_lshlrev_b32_e32 v190, 16, v120
	v_lshlrev_b32_e32 v191, 16, v121
	v_and_b32_e32 v114, 0xffff0000, v118
	v_and_b32_e32 v115, 0xffff0000, v119
	v_and_b32_e32 v116, 0xffff0000, v120
	v_and_b32_e32 v117, 0xffff0000, v121
	v_mul_f32_e32 v114, v114, v114
	v_mul_f32_e32 v115, v115, v115
	v_mul_f32_e32 v116, v116, v116
	v_mul_f32_e32 v117, v117, v117
	v_fmac_f32_e32 v114, v188, v188
	v_fmac_f32_e32 v115, v189, v189
	v_fmac_f32_e32 v116, v190, v190
	v_fmac_f32_e32 v117, v191, v191
	v_add_f32_e32 v114, v114, v115
	v_add_f32_e32 v114, v114, v116
	v_add_f32_e32 v114, v114, v117
	v_add_f32_e32 v122, v122, v114
	v_add_u32_e32 v151, 0x8000, v151
	s_waitcnt vmcnt(15)
	v_lshlrev_b32_e32 v182, 16, v192
	v_and_b32_e32 v183, 0xffff0000, v192
	v_pk_add_f32 v[110:111], v[110:111], v[182:183]
	v_lshlrev_b32_e32 v248, 16, v193
	v_and_b32_e32 v249, 0xffff0000, v193
	v_pk_add_f32 v[112:113], v[112:113], v[248:249]
	v_lshlrev_b32_e32 v138, 16, v194
	v_and_b32_e32 v139, 0xffff0000, v194
	v_pk_add_f32 v[106:107], v[106:107], v[138:139]
	v_lshlrev_b32_e32 v182, 16, v195
	v_and_b32_e32 v183, 0xffff0000, v195
	v_pk_add_f32 v[108:109], v[108:109], v[182:183]
	v_cvt_pk_bf16_f32 v110, v110, v111
	v_cvt_pk_bf16_f32 v111, v112, v113
	v_cvt_pk_bf16_f32 v112, v106, v107
	v_cvt_pk_bf16_f32 v113, v108, v109
	global_store_dwordx4 v151, v[110:113], s[74:75]
	v_lshlrev_b32_e32 v192, 16, v110
	v_lshlrev_b32_e32 v193, 16, v111
	v_lshlrev_b32_e32 v194, 16, v112
	v_lshlrev_b32_e32 v195, 16, v113
	v_and_b32_e32 v106, 0xffff0000, v110
	v_and_b32_e32 v107, 0xffff0000, v111
	v_and_b32_e32 v108, 0xffff0000, v112
	v_and_b32_e32 v109, 0xffff0000, v113
	v_mul_f32_e32 v106, v106, v106
	v_mul_f32_e32 v107, v107, v107
	v_mul_f32_e32 v108, v108, v108
	v_mul_f32_e32 v109, v109, v109
	v_fmac_f32_e32 v106, v192, v192
	v_fmac_f32_e32 v107, v193, v193
	v_fmac_f32_e32 v108, v194, v194
	v_fmac_f32_e32 v109, v195, v195
	v_add_f32_e32 v106, v106, v107
	v_add_f32_e32 v106, v106, v108
	v_add_f32_e32 v106, v106, v109
	s_waitcnt vmcnt(15)
	v_lshlrev_b32_e32 v182, 16, v196
	v_and_b32_e32 v183, 0xffff0000, v196
	v_pk_add_f32 v[102:103], v[102:103], v[182:183]
	v_lshlrev_b32_e32 v248, 16, v197
	v_and_b32_e32 v249, 0xffff0000, v197
	v_pk_add_f32 v[104:105], v[104:105], v[248:249]
	v_lshlrev_b32_e32 v138, 16, v198
	v_and_b32_e32 v139, 0xffff0000, v198
	v_pk_add_f32 v[98:99], v[98:99], v[138:139]
	v_lshlrev_b32_e32 v182, 16, v199
	v_and_b32_e32 v183, 0xffff0000, v199
	v_pk_add_f32 v[100:101], v[100:101], v[182:183]
	v_cvt_pk_bf16_f32 v102, v102, v103
	v_cvt_pk_bf16_f32 v103, v104, v105
	v_cvt_pk_bf16_f32 v104, v98, v99
	v_cvt_pk_bf16_f32 v105, v100, v101
	global_store_dwordx4 v151, v[102:105], s[74:75] offset:256
	v_lshlrev_b32_e32 v196, 16, v102
	v_lshlrev_b32_e32 v197, 16, v103
	v_lshlrev_b32_e32 v198, 16, v104
	v_lshlrev_b32_e32 v199, 16, v105
	v_and_b32_e32 v98, 0xffff0000, v102
	v_and_b32_e32 v99, 0xffff0000, v103
	v_and_b32_e32 v100, 0xffff0000, v104
	v_and_b32_e32 v101, 0xffff0000, v105
	v_mul_f32_e32 v98, v98, v98
	v_mul_f32_e32 v99, v99, v99
	v_mul_f32_e32 v100, v100, v100
	v_mul_f32_e32 v101, v101, v101
	v_fmac_f32_e32 v98, v196, v196
	v_fmac_f32_e32 v99, v197, v197
	v_fmac_f32_e32 v100, v198, v198
	v_fmac_f32_e32 v101, v199, v199
	v_add_f32_e32 v98, v98, v99
	v_add_f32_e32 v98, v98, v100
	v_add_f32_e32 v98, v98, v101
	v_add_f32_e32 v106, v106, v98
	v_add_u32_e32 v151, 0x8000, v151
	s_waitcnt vmcnt(15)
	v_lshlrev_b32_e32 v182, 16, v200
	v_and_b32_e32 v183, 0xffff0000, v200
	v_pk_add_f32 v[94:95], v[94:95], v[182:183]
	v_lshlrev_b32_e32 v248, 16, v201
	v_and_b32_e32 v249, 0xffff0000, v201
	v_pk_add_f32 v[96:97], v[96:97], v[248:249]
	v_lshlrev_b32_e32 v138, 16, v202
	v_and_b32_e32 v139, 0xffff0000, v202
	v_pk_add_f32 v[90:91], v[90:91], v[138:139]
	v_lshlrev_b32_e32 v182, 16, v203
	v_and_b32_e32 v183, 0xffff0000, v203
	v_pk_add_f32 v[92:93], v[92:93], v[182:183]
	v_cvt_pk_bf16_f32 v94, v94, v95
	v_cvt_pk_bf16_f32 v95, v96, v97
	v_cvt_pk_bf16_f32 v96, v90, v91
	v_cvt_pk_bf16_f32 v97, v92, v93
	global_store_dwordx4 v151, v[94:97], s[74:75]
	v_lshlrev_b32_e32 v200, 16, v94
	v_lshlrev_b32_e32 v201, 16, v95
	v_lshlrev_b32_e32 v202, 16, v96
	v_lshlrev_b32_e32 v203, 16, v97
	v_and_b32_e32 v90, 0xffff0000, v94
	v_and_b32_e32 v91, 0xffff0000, v95
	v_and_b32_e32 v92, 0xffff0000, v96
	v_and_b32_e32 v93, 0xffff0000, v97
	v_mul_f32_e32 v90, v90, v90
	v_mul_f32_e32 v91, v91, v91
	v_mul_f32_e32 v92, v92, v92
	v_mul_f32_e32 v93, v93, v93
	v_fmac_f32_e32 v90, v200, v200
	v_fmac_f32_e32 v91, v201, v201
	v_fmac_f32_e32 v92, v202, v202
	v_fmac_f32_e32 v93, v203, v203
	v_add_f32_e32 v90, v90, v91
	v_add_f32_e32 v90, v90, v92
	v_add_f32_e32 v90, v90, v93
	s_waitcnt vmcnt(15)
	v_lshlrev_b32_e32 v182, 16, v204
	v_and_b32_e32 v183, 0xffff0000, v204
	v_pk_add_f32 v[86:87], v[86:87], v[182:183]
	v_lshlrev_b32_e32 v248, 16, v205
	v_and_b32_e32 v249, 0xffff0000, v205
	v_pk_add_f32 v[88:89], v[88:89], v[248:249]
	v_lshlrev_b32_e32 v138, 16, v206
	v_and_b32_e32 v139, 0xffff0000, v206
	v_pk_add_f32 v[82:83], v[82:83], v[138:139]
	v_lshlrev_b32_e32 v182, 16, v207
	v_and_b32_e32 v183, 0xffff0000, v207
	v_pk_add_f32 v[84:85], v[84:85], v[182:183]
	v_cvt_pk_bf16_f32 v86, v86, v87
	v_cvt_pk_bf16_f32 v87, v88, v89
	v_cvt_pk_bf16_f32 v88, v82, v83
	v_cvt_pk_bf16_f32 v89, v84, v85
	global_store_dwordx4 v151, v[86:89], s[74:75] offset:256
	v_lshlrev_b32_e32 v204, 16, v86
	v_lshlrev_b32_e32 v205, 16, v87
	v_lshlrev_b32_e32 v206, 16, v88
	v_lshlrev_b32_e32 v207, 16, v89
	v_and_b32_e32 v82, 0xffff0000, v86
	v_and_b32_e32 v83, 0xffff0000, v87
	v_and_b32_e32 v84, 0xffff0000, v88
	v_and_b32_e32 v85, 0xffff0000, v89
	v_mul_f32_e32 v82, v82, v82
	v_mul_f32_e32 v83, v83, v83
	v_mul_f32_e32 v84, v84, v84
	v_mul_f32_e32 v85, v85, v85
	v_fmac_f32_e32 v82, v204, v204
	v_fmac_f32_e32 v83, v205, v205
	v_fmac_f32_e32 v84, v206, v206
	v_fmac_f32_e32 v85, v207, v207
	v_add_f32_e32 v82, v82, v83
	v_add_f32_e32 v82, v82, v84
	v_add_f32_e32 v82, v82, v85
	v_add_f32_e32 v90, v90, v82
	v_add_u32_e32 v151, 0x8000, v151
	s_waitcnt vmcnt(15)
	v_lshlrev_b32_e32 v182, 16, v208
	v_and_b32_e32 v183, 0xffff0000, v208
	v_pk_add_f32 v[78:79], v[78:79], v[182:183]
	v_lshlrev_b32_e32 v248, 16, v209
	v_and_b32_e32 v249, 0xffff0000, v209
	v_pk_add_f32 v[80:81], v[80:81], v[248:249]
	v_lshlrev_b32_e32 v138, 16, v210
	v_and_b32_e32 v139, 0xffff0000, v210
	v_pk_add_f32 v[74:75], v[74:75], v[138:139]
	v_lshlrev_b32_e32 v182, 16, v211
	v_and_b32_e32 v183, 0xffff0000, v211
	v_pk_add_f32 v[76:77], v[76:77], v[182:183]
	v_cvt_pk_bf16_f32 v78, v78, v79
	v_cvt_pk_bf16_f32 v79, v80, v81
	v_cvt_pk_bf16_f32 v80, v74, v75
	v_cvt_pk_bf16_f32 v81, v76, v77
	global_store_dwordx4 v151, v[78:81], s[74:75]
	v_lshlrev_b32_e32 v208, 16, v78
	v_lshlrev_b32_e32 v209, 16, v79
	v_lshlrev_b32_e32 v210, 16, v80
	v_lshlrev_b32_e32 v211, 16, v81
	v_and_b32_e32 v74, 0xffff0000, v78
	v_and_b32_e32 v75, 0xffff0000, v79
	v_and_b32_e32 v76, 0xffff0000, v80
	v_and_b32_e32 v77, 0xffff0000, v81
	v_mul_f32_e32 v74, v74, v74
	v_mul_f32_e32 v75, v75, v75
	v_mul_f32_e32 v76, v76, v76
	v_mul_f32_e32 v77, v77, v77
	v_fmac_f32_e32 v74, v208, v208
	v_fmac_f32_e32 v75, v209, v209
	v_fmac_f32_e32 v76, v210, v210
	v_fmac_f32_e32 v77, v211, v211
	v_add_f32_e32 v74, v74, v75
	v_add_f32_e32 v74, v74, v76
	v_add_f32_e32 v74, v74, v77
	s_waitcnt vmcnt(15)
	v_lshlrev_b32_e32 v182, 16, v212
	v_and_b32_e32 v183, 0xffff0000, v212
	v_pk_add_f32 v[70:71], v[70:71], v[182:183]
	v_lshlrev_b32_e32 v248, 16, v213
	v_and_b32_e32 v249, 0xffff0000, v213
	v_pk_add_f32 v[72:73], v[72:73], v[248:249]
	v_lshlrev_b32_e32 v138, 16, v214
	v_and_b32_e32 v139, 0xffff0000, v214
	v_pk_add_f32 v[66:67], v[66:67], v[138:139]
	v_lshlrev_b32_e32 v182, 16, v215
	v_and_b32_e32 v183, 0xffff0000, v215
	v_pk_add_f32 v[68:69], v[68:69], v[182:183]
	v_cvt_pk_bf16_f32 v70, v70, v71
	v_cvt_pk_bf16_f32 v71, v72, v73
	v_cvt_pk_bf16_f32 v72, v66, v67
	v_cvt_pk_bf16_f32 v73, v68, v69
	global_store_dwordx4 v151, v[70:73], s[74:75] offset:256
	v_lshlrev_b32_e32 v212, 16, v70
	v_lshlrev_b32_e32 v213, 16, v71
	v_lshlrev_b32_e32 v214, 16, v72
	v_lshlrev_b32_e32 v215, 16, v73
	v_and_b32_e32 v66, 0xffff0000, v70
	v_and_b32_e32 v67, 0xffff0000, v71
	v_and_b32_e32 v68, 0xffff0000, v72
	v_and_b32_e32 v69, 0xffff0000, v73
	v_mul_f32_e32 v66, v66, v66
	v_mul_f32_e32 v67, v67, v67
	v_mul_f32_e32 v68, v68, v68
	v_mul_f32_e32 v69, v69, v69
	v_fmac_f32_e32 v66, v212, v212
	v_fmac_f32_e32 v67, v213, v213
	v_fmac_f32_e32 v68, v214, v214
	v_fmac_f32_e32 v69, v215, v215
	v_add_f32_e32 v66, v66, v67
	v_add_f32_e32 v66, v66, v68
	v_add_f32_e32 v66, v66, v69
	v_add_f32_e32 v74, v74, v66
	v_add_u32_e32 v151, 0x28000, v151
	s_waitcnt vmcnt(15)
	v_lshlrev_b32_e32 v182, 16, v216
	v_and_b32_e32 v183, 0xffff0000, v216
	v_pk_add_f32 v[60:61], v[60:61], v[182:183]
	v_lshlrev_b32_e32 v248, 16, v217
	v_and_b32_e32 v249, 0xffff0000, v217
	v_pk_add_f32 v[62:63], v[62:63], v[248:249]
	v_lshlrev_b32_e32 v138, 16, v218
	v_and_b32_e32 v139, 0xffff0000, v218
	v_pk_add_f32 v[56:57], v[56:57], v[138:139]
	v_lshlrev_b32_e32 v182, 16, v219
	v_and_b32_e32 v183, 0xffff0000, v219
	v_pk_add_f32 v[58:59], v[58:59], v[182:183]
	v_cvt_pk_bf16_f32 v60, v60, v61
	v_cvt_pk_bf16_f32 v61, v62, v63
	v_cvt_pk_bf16_f32 v62, v56, v57
	v_cvt_pk_bf16_f32 v63, v58, v59
	global_store_dwordx4 v151, v[60:63], s[74:75]
	v_lshlrev_b32_e32 v216, 16, v60
	v_lshlrev_b32_e32 v217, 16, v61
	v_lshlrev_b32_e32 v218, 16, v62
	v_lshlrev_b32_e32 v219, 16, v63
	v_and_b32_e32 v56, 0xffff0000, v60
	v_and_b32_e32 v57, 0xffff0000, v61
	v_and_b32_e32 v58, 0xffff0000, v62
	v_and_b32_e32 v59, 0xffff0000, v63
	v_mul_f32_e32 v56, v56, v56
	v_mul_f32_e32 v57, v57, v57
	v_mul_f32_e32 v58, v58, v58
	v_mul_f32_e32 v59, v59, v59
	v_fmac_f32_e32 v56, v216, v216
	v_fmac_f32_e32 v57, v217, v217
	v_fmac_f32_e32 v58, v218, v218
	v_fmac_f32_e32 v59, v219, v219
	v_add_f32_e32 v56, v56, v57
	v_add_f32_e32 v56, v56, v58
	v_add_f32_e32 v56, v56, v59
	s_waitcnt vmcnt(15)
	v_lshlrev_b32_e32 v182, 16, v220
	v_and_b32_e32 v183, 0xffff0000, v220
	v_pk_add_f32 v[52:53], v[52:53], v[182:183]
	v_lshlrev_b32_e32 v248, 16, v221
	v_and_b32_e32 v249, 0xffff0000, v221
	v_pk_add_f32 v[54:55], v[54:55], v[248:249]
	v_lshlrev_b32_e32 v138, 16, v222
	v_and_b32_e32 v139, 0xffff0000, v222
	v_pk_add_f32 v[48:49], v[48:49], v[138:139]
	v_lshlrev_b32_e32 v182, 16, v223
	v_and_b32_e32 v183, 0xffff0000, v223
	v_pk_add_f32 v[50:51], v[50:51], v[182:183]
	v_cvt_pk_bf16_f32 v52, v52, v53
	v_cvt_pk_bf16_f32 v53, v54, v55
	v_cvt_pk_bf16_f32 v54, v48, v49
	v_cvt_pk_bf16_f32 v55, v50, v51
	global_store_dwordx4 v151, v[52:55], s[74:75] offset:256
	v_lshlrev_b32_e32 v220, 16, v52
	v_lshlrev_b32_e32 v221, 16, v53
	v_lshlrev_b32_e32 v222, 16, v54
	v_lshlrev_b32_e32 v223, 16, v55
	v_and_b32_e32 v48, 0xffff0000, v52
	v_and_b32_e32 v49, 0xffff0000, v53
	v_and_b32_e32 v50, 0xffff0000, v54
	v_and_b32_e32 v51, 0xffff0000, v55
	v_mul_f32_e32 v48, v48, v48
	v_mul_f32_e32 v49, v49, v49
	v_mul_f32_e32 v50, v50, v50
	v_mul_f32_e32 v51, v51, v51
	v_fmac_f32_e32 v48, v220, v220
	v_fmac_f32_e32 v49, v221, v221
	v_fmac_f32_e32 v50, v222, v222
	v_fmac_f32_e32 v51, v223, v223
	v_add_f32_e32 v48, v48, v49
	v_add_f32_e32 v48, v48, v50
	v_add_f32_e32 v48, v48, v51
	v_add_f32_e32 v56, v56, v48
	v_add_u32_e32 v151, 0x8000, v151
	s_waitcnt vmcnt(15)
	v_lshlrev_b32_e32 v182, 16, v224
	v_and_b32_e32 v183, 0xffff0000, v224
	v_pk_add_f32 v[44:45], v[44:45], v[182:183]
	v_lshlrev_b32_e32 v248, 16, v225
	v_and_b32_e32 v249, 0xffff0000, v225
	v_pk_add_f32 v[46:47], v[46:47], v[248:249]
	v_lshlrev_b32_e32 v138, 16, v226
	v_and_b32_e32 v139, 0xffff0000, v226
	v_pk_add_f32 v[40:41], v[40:41], v[138:139]
	v_lshlrev_b32_e32 v182, 16, v227
	v_and_b32_e32 v183, 0xffff0000, v227
	v_pk_add_f32 v[42:43], v[42:43], v[182:183]
	v_cvt_pk_bf16_f32 v44, v44, v45
	v_cvt_pk_bf16_f32 v45, v46, v47
	v_cvt_pk_bf16_f32 v46, v40, v41
	v_cvt_pk_bf16_f32 v47, v42, v43
	global_store_dwordx4 v151, v[44:47], s[74:75]
	v_lshlrev_b32_e32 v224, 16, v44
	v_lshlrev_b32_e32 v225, 16, v45
	v_lshlrev_b32_e32 v226, 16, v46
	v_lshlrev_b32_e32 v227, 16, v47
	v_and_b32_e32 v40, 0xffff0000, v44
	v_and_b32_e32 v41, 0xffff0000, v45
	v_and_b32_e32 v42, 0xffff0000, v46
	v_and_b32_e32 v43, 0xffff0000, v47
	v_mul_f32_e32 v40, v40, v40
	v_mul_f32_e32 v41, v41, v41
	v_mul_f32_e32 v42, v42, v42
	v_mul_f32_e32 v43, v43, v43
	v_fmac_f32_e32 v40, v224, v224
	v_fmac_f32_e32 v41, v225, v225
	v_fmac_f32_e32 v42, v226, v226
	v_fmac_f32_e32 v43, v227, v227
	v_add_f32_e32 v40, v40, v41
	v_add_f32_e32 v40, v40, v42
	v_add_f32_e32 v40, v40, v43
	s_waitcnt vmcnt(15)
	v_lshlrev_b32_e32 v182, 16, v228
	v_and_b32_e32 v183, 0xffff0000, v228
	v_pk_add_f32 v[36:37], v[36:37], v[182:183]
	v_lshlrev_b32_e32 v248, 16, v229
	v_and_b32_e32 v249, 0xffff0000, v229
	v_pk_add_f32 v[38:39], v[38:39], v[248:249]
	v_lshlrev_b32_e32 v138, 16, v230
	v_and_b32_e32 v139, 0xffff0000, v230
	v_pk_add_f32 v[32:33], v[32:33], v[138:139]
	v_lshlrev_b32_e32 v182, 16, v231
	v_and_b32_e32 v183, 0xffff0000, v231
	v_pk_add_f32 v[34:35], v[34:35], v[182:183]
	v_cvt_pk_bf16_f32 v36, v36, v37
	v_cvt_pk_bf16_f32 v37, v38, v39
	v_cvt_pk_bf16_f32 v38, v32, v33
	v_cvt_pk_bf16_f32 v39, v34, v35
	global_store_dwordx4 v151, v[36:39], s[74:75] offset:256
	v_lshlrev_b32_e32 v228, 16, v36
	v_lshlrev_b32_e32 v229, 16, v37
	v_lshlrev_b32_e32 v230, 16, v38
	v_lshlrev_b32_e32 v231, 16, v39
	v_and_b32_e32 v32, 0xffff0000, v36
	v_and_b32_e32 v33, 0xffff0000, v37
	v_and_b32_e32 v34, 0xffff0000, v38
	v_and_b32_e32 v35, 0xffff0000, v39
	v_mul_f32_e32 v32, v32, v32
	v_mul_f32_e32 v33, v33, v33
	v_mul_f32_e32 v34, v34, v34
	v_mul_f32_e32 v35, v35, v35
	v_fmac_f32_e32 v32, v228, v228
	v_fmac_f32_e32 v33, v229, v229
	v_fmac_f32_e32 v34, v230, v230
	v_fmac_f32_e32 v35, v231, v231
	v_add_f32_e32 v32, v32, v33
	v_add_f32_e32 v32, v32, v34
	v_add_f32_e32 v32, v32, v35
	v_add_f32_e32 v40, v40, v32
	v_add_u32_e32 v151, 0x8000, v151
	s_waitcnt vmcnt(15)
	v_lshlrev_b32_e32 v182, 16, v232
	v_and_b32_e32 v183, 0xffff0000, v232
	v_pk_add_f32 v[28:29], v[28:29], v[182:183]
	v_lshlrev_b32_e32 v248, 16, v233
	v_and_b32_e32 v249, 0xffff0000, v233
	v_pk_add_f32 v[30:31], v[30:31], v[248:249]
	v_lshlrev_b32_e32 v138, 16, v234
	v_and_b32_e32 v139, 0xffff0000, v234
	v_pk_add_f32 v[24:25], v[24:25], v[138:139]
	v_lshlrev_b32_e32 v182, 16, v235
	v_and_b32_e32 v183, 0xffff0000, v235
	v_pk_add_f32 v[26:27], v[26:27], v[182:183]
	v_cvt_pk_bf16_f32 v28, v28, v29
	v_cvt_pk_bf16_f32 v29, v30, v31
	v_cvt_pk_bf16_f32 v30, v24, v25
	v_cvt_pk_bf16_f32 v31, v26, v27
	global_store_dwordx4 v151, v[28:31], s[74:75]
	v_lshlrev_b32_e32 v232, 16, v28
	v_lshlrev_b32_e32 v233, 16, v29
	v_lshlrev_b32_e32 v234, 16, v30
	v_lshlrev_b32_e32 v235, 16, v31
	v_and_b32_e32 v24, 0xffff0000, v28
	v_and_b32_e32 v25, 0xffff0000, v29
	v_and_b32_e32 v26, 0xffff0000, v30
	v_and_b32_e32 v27, 0xffff0000, v31
	v_mul_f32_e32 v24, v24, v24
	v_mul_f32_e32 v25, v25, v25
	v_mul_f32_e32 v26, v26, v26
	v_mul_f32_e32 v27, v27, v27
	v_fmac_f32_e32 v24, v232, v232
	v_fmac_f32_e32 v25, v233, v233
	v_fmac_f32_e32 v26, v234, v234
	v_fmac_f32_e32 v27, v235, v235
	v_add_f32_e32 v24, v24, v25
	v_add_f32_e32 v24, v24, v26
	v_add_f32_e32 v24, v24, v27
	s_waitcnt vmcnt(15)
	v_lshlrev_b32_e32 v182, 16, v236
	v_and_b32_e32 v183, 0xffff0000, v236
	v_pk_add_f32 v[20:21], v[20:21], v[182:183]
	v_lshlrev_b32_e32 v248, 16, v237
	v_and_b32_e32 v249, 0xffff0000, v237
	v_pk_add_f32 v[22:23], v[22:23], v[248:249]
	v_lshlrev_b32_e32 v138, 16, v238
	v_and_b32_e32 v139, 0xffff0000, v238
	v_pk_add_f32 v[16:17], v[16:17], v[138:139]
	v_lshlrev_b32_e32 v182, 16, v239
	v_and_b32_e32 v183, 0xffff0000, v239
	v_pk_add_f32 v[18:19], v[18:19], v[182:183]
	v_cvt_pk_bf16_f32 v20, v20, v21
	v_cvt_pk_bf16_f32 v21, v22, v23
	v_cvt_pk_bf16_f32 v22, v16, v17
	v_cvt_pk_bf16_f32 v23, v18, v19
	global_store_dwordx4 v151, v[20:23], s[74:75] offset:256
	v_lshlrev_b32_e32 v236, 16, v20
	v_lshlrev_b32_e32 v237, 16, v21
	v_lshlrev_b32_e32 v238, 16, v22
	v_lshlrev_b32_e32 v239, 16, v23
	v_and_b32_e32 v16, 0xffff0000, v20
	v_and_b32_e32 v17, 0xffff0000, v21
	v_and_b32_e32 v18, 0xffff0000, v22
	v_and_b32_e32 v19, 0xffff0000, v23
	v_mul_f32_e32 v16, v16, v16
	v_mul_f32_e32 v17, v17, v17
	v_mul_f32_e32 v18, v18, v18
	v_mul_f32_e32 v19, v19, v19
	v_fmac_f32_e32 v16, v236, v236
	v_fmac_f32_e32 v17, v237, v237
	v_fmac_f32_e32 v18, v238, v238
	v_fmac_f32_e32 v19, v239, v239
	v_add_f32_e32 v16, v16, v17
	v_add_f32_e32 v16, v16, v18
	v_add_f32_e32 v16, v16, v19
	v_add_f32_e32 v24, v24, v16
	v_add_u32_e32 v151, 0x8000, v151
	s_waitcnt vmcnt(15)
	v_lshlrev_b32_e32 v182, 16, v240
	v_and_b32_e32 v183, 0xffff0000, v240
	v_pk_add_f32 v[12:13], v[12:13], v[182:183]
	v_lshlrev_b32_e32 v248, 16, v241
	v_and_b32_e32 v249, 0xffff0000, v241
	v_pk_add_f32 v[14:15], v[14:15], v[248:249]
	v_lshlrev_b32_e32 v138, 16, v242
	v_and_b32_e32 v139, 0xffff0000, v242
	v_pk_add_f32 v[8:9], v[8:9], v[138:139]
	v_lshlrev_b32_e32 v182, 16, v243
	v_and_b32_e32 v183, 0xffff0000, v243
	v_pk_add_f32 v[10:11], v[10:11], v[182:183]
	v_cvt_pk_bf16_f32 v12, v12, v13
	v_cvt_pk_bf16_f32 v13, v14, v15
	v_cvt_pk_bf16_f32 v14, v8, v9
	v_cvt_pk_bf16_f32 v15, v10, v11
	global_store_dwordx4 v151, v[12:15], s[74:75]
	v_lshlrev_b32_e32 v240, 16, v12
	v_lshlrev_b32_e32 v241, 16, v13
	v_lshlrev_b32_e32 v242, 16, v14
	v_lshlrev_b32_e32 v243, 16, v15
	v_and_b32_e32 v8, 0xffff0000, v12
	v_and_b32_e32 v9, 0xffff0000, v13
	v_and_b32_e32 v10, 0xffff0000, v14
	v_and_b32_e32 v11, 0xffff0000, v15
	v_mul_f32_e32 v8, v8, v8
	v_mul_f32_e32 v9, v9, v9
	v_mul_f32_e32 v10, v10, v10
	v_mul_f32_e32 v11, v11, v11
	v_fmac_f32_e32 v8, v240, v240
	v_fmac_f32_e32 v9, v241, v241
	v_fmac_f32_e32 v10, v242, v242
	v_fmac_f32_e32 v11, v243, v243
	v_add_f32_e32 v8, v8, v9
	v_add_f32_e32 v8, v8, v10
	v_add_f32_e32 v8, v8, v11
	s_waitcnt vmcnt(15)
	v_lshlrev_b32_e32 v182, 16, v244
	v_and_b32_e32 v183, 0xffff0000, v244
	v_pk_add_f32 v[4:5], v[4:5], v[182:183]
	v_lshlrev_b32_e32 v248, 16, v245
	v_and_b32_e32 v249, 0xffff0000, v245
	v_pk_add_f32 v[6:7], v[6:7], v[248:249]
	v_lshlrev_b32_e32 v138, 16, v246
	v_and_b32_e32 v139, 0xffff0000, v246
	v_pk_add_f32 v[0:1], v[0:1], v[138:139]
	v_lshlrev_b32_e32 v182, 16, v247
	v_and_b32_e32 v183, 0xffff0000, v247
	v_pk_add_f32 v[2:3], v[2:3], v[182:183]
	v_cvt_pk_bf16_f32 v4, v4, v5
	v_cvt_pk_bf16_f32 v5, v6, v7
	v_cvt_pk_bf16_f32 v6, v0, v1
	v_cvt_pk_bf16_f32 v7, v2, v3
	global_store_dwordx4 v151, v[4:7], s[74:75] offset:256
	v_lshlrev_b32_e32 v244, 16, v4
	v_lshlrev_b32_e32 v245, 16, v5
	v_lshlrev_b32_e32 v246, 16, v6
	v_lshlrev_b32_e32 v247, 16, v7
	v_and_b32_e32 v0, 0xffff0000, v4
	v_and_b32_e32 v1, 0xffff0000, v5
	v_and_b32_e32 v2, 0xffff0000, v6
	v_and_b32_e32 v3, 0xffff0000, v7
	v_mul_f32_e32 v0, v0, v0
	v_mul_f32_e32 v1, v1, v1
	v_mul_f32_e32 v2, v2, v2
	v_mul_f32_e32 v3, v3, v3
	v_fmac_f32_e32 v0, v244, v244
	v_fmac_f32_e32 v1, v245, v245
	v_fmac_f32_e32 v2, v246, v246
	v_fmac_f32_e32 v3, v247, v247
	v_add_f32_e32 v0, v0, v1
	v_add_f32_e32 v0, v0, v2
	v_add_f32_e32 v0, v0, v3
	v_add_f32_e32 v8, v8, v0
	v_mov_b32_e32 v175, v122
	s_nop 1
	v_permlane16_swap_b32_e32 v175, v122
	v_add_f32_e32 v122, v175, v122
	v_mov_b32_e32 v175, v106
	s_nop 1
	v_permlane16_swap_b32_e32 v175, v106
	v_add_f32_e32 v106, v175, v106
	v_mov_b32_e32 v175, v90
	s_nop 1
	v_permlane16_swap_b32_e32 v175, v90
	v_add_f32_e32 v90, v175, v90
	v_mov_b32_e32 v175, v74
	s_nop 1
	v_permlane16_swap_b32_e32 v175, v74
	v_add_f32_e32 v74, v175, v74
	v_mov_b32_e32 v175, v56
	s_nop 1
	v_permlane16_swap_b32_e32 v175, v56
	v_add_f32_e32 v56, v175, v56
	v_mov_b32_e32 v175, v40
	s_nop 1
	v_permlane16_swap_b32_e32 v175, v40
	v_add_f32_e32 v40, v175, v40
	v_mov_b32_e32 v175, v24
	s_nop 1
	v_permlane16_swap_b32_e32 v175, v24
	v_add_f32_e32 v24, v175, v24
	v_mov_b32_e32 v175, v8
	s_nop 1
	v_permlane16_swap_b32_e32 v175, v8
	v_add_f32_e32 v8, v175, v8
	v_mov_b32_e32 v175, v122
	s_nop 1
	v_permlane32_swap_b32_e32 v175, v122
	v_add_f32_e32 v122, v175, v122
	v_mov_b32_e32 v175, v106
	s_nop 1
	v_permlane32_swap_b32_e32 v175, v106
	v_add_f32_e32 v106, v175, v106
	v_mov_b32_e32 v175, v90
	s_nop 1
	v_permlane32_swap_b32_e32 v175, v90
	v_add_f32_e32 v90, v175, v90
	v_mov_b32_e32 v175, v74
	s_nop 1
	v_permlane32_swap_b32_e32 v175, v74
	v_add_f32_e32 v74, v175, v74
	v_mov_b32_e32 v175, v56
	s_nop 1
	v_permlane32_swap_b32_e32 v175, v56
	v_add_f32_e32 v56, v175, v56
	v_mov_b32_e32 v175, v40
	s_nop 1
	v_permlane32_swap_b32_e32 v175, v40
	v_add_f32_e32 v40, v175, v40
	v_mov_b32_e32 v175, v24
	s_nop 1
	v_permlane32_swap_b32_e32 v175, v24
	v_add_f32_e32 v24, v175, v24
	v_mov_b32_e32 v175, v8
	s_nop 1
	v_permlane32_swap_b32_e32 v175, v8
	v_add_f32_e32 v8, v175, v8
	s_add_u32 s74, s28, s56
	s_addc_u32 s75, s29, 0
	s_and_saveexec_b64 s[4:5], s[38:39]
	s_nop 1
	global_store_dword v149, v122, s[74:75]
	v_add_u32_e32 v149, 0x400, v149
	global_store_dword v149, v106, s[74:75]
	v_add_u32_e32 v149, 0x400, v149
	global_store_dword v149, v90, s[74:75]
	v_add_u32_e32 v149, 0x400, v149
	global_store_dword v149, v74, s[74:75]
	v_add_u32_e32 v149, 0x1400, v149
	global_store_dword v149, v56, s[74:75]
	v_add_u32_e32 v149, 0x400, v149
	global_store_dword v149, v40, s[74:75]
	v_add_u32_e32 v149, 0x400, v149
	global_store_dword v149, v24, s[74:75]
	v_add_u32_e32 v149, 0x400, v149
	global_store_dword v149, v8, s[74:75]
	s_or_b64 exec, exec, s[4:5]
	s_mov_b32 s56, s57
	s_mov_b32 s57, 0
	s_lshl_b32 s76, s24, 2
	v_readlane_b32 s74, v255, 32
	v_readlane_b32 s75, v255, 33
	s_movk_i32 s78, 0xf800
	v_readlane_b32 s70, v255, 26
	v_readlane_b32 s71, v255, 27
	s_branch .Lxo_done
	v_lshl_add_u32 v150, s29, 8, v172
	s_lshl_b32 s4, s28, 8
	v_ashrrev_i32_e32 v151, 31, v150
	s_ashr_i32 s5, s4, 31
	v_lshlrev_b64 v[138:139], 11, v[150:151]
	v_mov_b32_e32 v149, s5
	v_or_b32_e32 v148, s4, v142
	v_lshl_add_u64 v[138:139], s[30:31], 0, v[138:139]
	v_lshl_add_u64 v[138:139], v[148:149], 1, v[138:139]
	global_load_dwordx4 v[184:187], v[138:139], off
	s_lshl_b32 s56, s28, 2
	s_ashr_i32 s57, s56, 31
	s_waitcnt vmcnt(0)
	v_lshlrev_b32_e32 v182, 16, v184
	v_and_b32_e32 v183, 0xffff0000, v184
	v_lshlrev_b32_e32 v184, 16, v185
	v_and_b32_e32 v185, 0xffff0000, v185
	v_lshlrev_b32_e32 v188, 16, v186
	v_and_b32_e32 v189, 0xffff0000, v186
	v_lshlrev_b32_e32 v186, 16, v187
	v_and_b32_e32 v187, 0xffff0000, v187
	v_pk_add_f32 v[126:127], v[126:127], v[182:183]
	v_pk_add_f32 v[128:129], v[128:129], v[184:185]
	v_pk_add_f32 v[182:183], v[124:125], v[186:187]
	v_pk_add_f32 v[122:123], v[122:123], v[188:189]
	v_cvt_pk_bf16_f32 v124, v126, v127
	v_cvt_pk_bf16_f32 v125, v128, v129
	s_nop 0
	v_cvt_pk_bf16_f32 v126, v122, v123
	v_cvt_pk_bf16_f32 v127, v182, v183
	global_load_dwordx4 v[184:187], v[138:139], off offset:256
	v_lshlrev_b32_e32 v128, 16, v124
	global_store_dwordx4 v[138:139], v[124:127], off
	v_lshlrev_b32_e32 v129, 16, v125
	v_lshlrev_b32_e32 v175, 16, v126
	v_and_b32_e32 v124, 0xffff0000, v124
	v_and_b32_e32 v125, 0xffff0000, v125
	v_and_b32_e32 v126, 0xffff0000, v126
	v_mul_f32_e32 v124, v124, v124
	v_mul_f32_e32 v125, v125, v125
	v_lshlrev_b32_e32 v182, 16, v127
	v_and_b32_e32 v127, 0xffff0000, v127
	v_mul_f32_e32 v126, v126, v126
	v_fmac_f32_e32 v124, v128, v128
	v_fmac_f32_e32 v125, v129, v129
	v_mul_f32_e32 v127, v127, v127
	v_fmac_f32_e32 v126, v175, v175
	v_add_f32_e32 v124, v124, v125
	v_fmac_f32_e32 v127, v182, v182
	v_add_f32_e32 v124, v124, v126
	v_add_f32_e32 v175, v124, v127
	v_and_b32_e32 v123, 64, v178
	v_xor_b32_e32 v122, 16, v178
	v_add_u32_e32 v123, 64, v123
	v_cmp_lt_i32_e32 vcc, v122, v123
	s_waitcnt vmcnt(1)
	v_lshlrev_b32_e32 v124, 16, v184
	v_and_b32_e32 v125, 0xffff0000, v184
	v_lshlrev_b32_e32 v126, 16, v185
	v_and_b32_e32 v127, 0xffff0000, v185
	v_lshlrev_b32_e32 v128, 16, v186
	v_and_b32_e32 v129, 0xffff0000, v186
	v_lshlrev_b32_e32 v182, 16, v187
	v_and_b32_e32 v183, 0xffff0000, v187
	v_pk_add_f32 v[120:121], v[120:121], v[126:127]
	v_pk_add_f32 v[118:119], v[118:119], v[124:125]
	v_pk_add_f32 v[116:117], v[116:117], v[182:183]
	v_pk_add_f32 v[114:115], v[114:115], v[128:129]
	v_cvt_pk_bf16_f32 v118, v118, v119
	v_cvt_pk_bf16_f32 v119, v120, v121
	v_cndmask_b32_e32 v122, v178, v122, vcc
	v_cvt_pk_bf16_f32 v120, v114, v115
	v_cvt_pk_bf16_f32 v121, v116, v117
	v_and_b32_e32 v115, 0xffff0000, v118
	v_and_b32_e32 v117, 0xffff0000, v119
	v_lshlrev_b32_e32 v114, 16, v118
	v_lshlrev_b32_e32 v116, 16, v119
	v_and_b32_e32 v125, 0xffff0000, v120
	v_mul_f32_e32 v115, v115, v115
	v_mul_f32_e32 v117, v117, v117
	v_lshlrev_b32_e32 v124, 16, v120
	v_and_b32_e32 v127, 0xffff0000, v121
	v_mul_f32_e32 v125, v125, v125
	v_fmac_f32_e32 v115, v114, v114
	v_fmac_f32_e32 v117, v116, v116
	v_lshlrev_b32_e32 v126, 16, v121
	v_mul_f32_e32 v127, v127, v127
	v_fmac_f32_e32 v125, v124, v124
	v_add_f32_e32 v114, v115, v117
	v_fmac_f32_e32 v127, v126, v126
	v_add_f32_e32 v114, v114, v125
	v_add_f32_e32 v114, v114, v127
	v_lshlrev_b32_e32 v122, 2, v122
	v_add_f32_e32 v114, v175, v114
	ds_bpermute_b32 v115, v122, v114
	v_xor_b32_e32 v116, 32, v178
	v_cmp_lt_i32_e32 vcc, v116, v123
	global_store_dwordx4 v[138:139], v[118:121], off offset:256
	s_waitcnt lgkmcnt(0)
	v_add_f32_e32 v114, v114, v115
	v_cndmask_b32_e32 v116, v178, v116, vcc
	v_lshlrev_b32_e32 v116, 2, v116
	ds_bpermute_b32 v115, v116, v114
	s_and_saveexec_b64 s[4:5], s[38:39]
	v_readlane_b32 s74, v255, 32
	v_readlane_b32 s75, v255, 33
	s_movk_i32 s78, 0xf800
	s_cbranch_execz .LBB0_112
	v_readlane_b32 s28, v250, 26
	s_waitcnt lgkmcnt(0)
	v_add_f32_e32 v117, v114, v115
	v_lshlrev_b64 v[114:115], 6, v[150:151]
	v_readlane_b32 s29, v250, 27
	s_lshl_b32 s76, s24, 2
	s_nop 0
	v_lshl_add_u64 v[114:115], s[28:29], 0, v[114:115]
	v_lshl_add_u64 v[114:115], s[56:57], 2, v[114:115]
	v_lshl_add_u64 v[114:115], v[114:115], 0, s[76:77]
	global_store_dword v[114:115], v117, off

.LBB0_149:
	v_readlane_b32 s4, v250, 25
	v_mbcnt_lo_u32_b32 v138, -1, 0
	v_mbcnt_hi_u32_b32 v138, -1, v138
	s_nop 1
	s_lshr_b32 s5, s4, 8
	s_bfe_u32 s4, s4, 0x20006
	v_and_b32_e32 v139, 15, v138
	v_lshrrev_b32_e32 v148, 4, v138
	s_lshl_b32 s70, s29, 8
	s_lshl_b32 s5, s5, 6
	s_add_u32 s5, s5, s70
	v_add_u32_e32 v139, s5, v139
	v_lshlrev_b32_e32 v149, 6, v139
	v_lshlrev_b32_e32 v150, 11, v139
	v_lshl_add_u32 v150, v148, 4, v150
	s_lshl_b32 s71, s4, 6
	v_add_u32_e32 v150, s71, v150
	v_lshlrev_b32_e32 v151, 12, v139
	v_lshl_add_u32 v151, v148, 5, v151
	s_lshl_b32 s71, s4, 7
	v_add_u32_e32 v151, s71, v151
	s_lshl_b32 s76, s28, 9
	s_add_u32 s74, s30, s76
	s_addc_u32 s75, s31, 0
	s_lshl_b32 s76, s28, 10
	s_add_u32 s70, s8, s76
	s_addc_u32 s71, s9, 0
	s_lshl_b32 s55, s28, 2
	s_lshl_b32 s54, s28, 4
	s_lshl_b32 s76, s4, 2
	s_add_u32 s54, s54, s76
	v_readlane_b32 s28, v250, 40
	v_readlane_b32 s29, v250, 41
	global_load_dwordx4 v[184:187], v150, s[74:75]
	global_load_dwordx4 v[188:191], v150, s[74:75] offset:256
	v_add_u32_e32 v150, 0x8000, v150
	global_load_dwordx4 v[192:195], v150, s[74:75]
	global_load_dwordx4 v[196:199], v150, s[74:75] offset:256
	v_add_u32_e32 v150, 0x8000, v150
	global_load_dwordx4 v[200:203], v150, s[74:75]
	global_load_dwordx4 v[204:207], v150, s[74:75] offset:256
	v_add_u32_e32 v150, 0x8000, v150
	global_load_dwordx4 v[208:211], v150, s[74:75]
	global_load_dwordx4 v[212:215], v150, s[74:75] offset:256
	v_add_u32_e32 v150, 0x28000, v150
	global_load_dwordx4 v[216:219], v150, s[74:75]
	global_load_dwordx4 v[220:223], v150, s[74:75] offset:256
	v_add_u32_e32 v150, 0x8000, v150
	global_load_dwordx4 v[224:227], v150, s[74:75]
	global_load_dwordx4 v[228:231], v150, s[74:75] offset:256
	v_add_u32_e32 v150, 0x8000, v150
	global_load_dwordx4 v[232:235], v150, s[74:75]
	global_load_dwordx4 v[236:239], v150, s[74:75] offset:256
	v_add_u32_e32 v150, 0x8000, v150
	global_load_dwordx4 v[240:243], v150, s[74:75]
	global_load_dwordx4 v[244:247], v150, s[74:75] offset:256
	s_waitcnt vmcnt(15)
	v_lshlrev_b32_e32 v182, 16, v184
	v_and_b32_e32 v183, 0xffff0000, v184
	v_pk_add_f32 v[126:127], v[126:127], v[182:183]
	v_lshlrev_b32_e32 v248, 16, v185
	v_and_b32_e32 v249, 0xffff0000, v185
	v_pk_add_f32 v[128:129], v[128:129], v[248:249]
	v_lshlrev_b32_e32 v138, 16, v186
	v_and_b32_e32 v139, 0xffff0000, v186
	v_pk_add_f32 v[122:123], v[122:123], v[138:139]
	v_lshlrev_b32_e32 v182, 16, v187
	v_and_b32_e32 v183, 0xffff0000, v187
	v_pk_add_f32 v[124:125], v[124:125], v[182:183]
	global_store_dwordx4 v151, v[126:129], s[70:71]
	global_store_dwordx4 v151, v[122:125], s[70:71] offset:16
	v_mul_f32_e32 v184, v127, v127
	v_mul_f32_e32 v185, v129, v129
	v_mul_f32_e32 v186, v123, v123
	v_mul_f32_e32 v187, v125, v125
	v_fmac_f32_e32 v184, v126, v126
	v_fmac_f32_e32 v185, v128, v128
	v_fmac_f32_e32 v186, v122, v122
	v_fmac_f32_e32 v187, v124, v124
	v_add_f32_e32 v184, v184, v185
	v_add_f32_e32 v184, v184, v186
	v_add_f32_e32 v184, v184, v187
	s_waitcnt vmcnt(16)
	v_lshlrev_b32_e32 v182, 16, v188
	v_and_b32_e32 v183, 0xffff0000, v188
	v_pk_add_f32 v[118:119], v[118:119], v[182:183]
	v_lshlrev_b32_e32 v248, 16, v189
	v_and_b32_e32 v249, 0xffff0000, v189
	v_pk_add_f32 v[120:121], v[120:121], v[248:249]
	v_lshlrev_b32_e32 v138, 16, v190
	v_and_b32_e32 v139, 0xffff0000, v190
	v_pk_add_f32 v[114:115], v[114:115], v[138:139]
	v_lshlrev_b32_e32 v182, 16, v191
	v_and_b32_e32 v183, 0xffff0000, v191
	v_pk_add_f32 v[116:117], v[116:117], v[182:183]
	global_store_dwordx4 v151, v[118:121], s[70:71] offset:512
	global_store_dwordx4 v151, v[114:117], s[70:71] offset:528
	v_mul_f32_e32 v188, v119, v119
	v_mul_f32_e32 v189, v121, v121
	v_mul_f32_e32 v190, v115, v115
	v_mul_f32_e32 v191, v117, v117
	v_fmac_f32_e32 v188, v118, v118
	v_fmac_f32_e32 v189, v120, v120
	v_fmac_f32_e32 v190, v114, v114
	v_fmac_f32_e32 v191, v116, v116
	v_add_f32_e32 v188, v188, v189
	v_add_f32_e32 v188, v188, v190
	v_add_f32_e32 v188, v188, v191
	v_add_f32_e32 v184, v184, v188
	v_add_u32_e32 v151, 0x10000, v151
	s_waitcnt vmcnt(17)
	v_lshlrev_b32_e32 v182, 16, v192
	v_and_b32_e32 v183, 0xffff0000, v192
	v_pk_add_f32 v[110:111], v[110:111], v[182:183]
	v_lshlrev_b32_e32 v248, 16, v193
	v_and_b32_e32 v249, 0xffff0000, v193
	v_pk_add_f32 v[112:113], v[112:113], v[248:249]
	v_lshlrev_b32_e32 v138, 16, v194
	v_and_b32_e32 v139, 0xffff0000, v194
	v_pk_add_f32 v[106:107], v[106:107], v[138:139]
	v_lshlrev_b32_e32 v182, 16, v195
	v_and_b32_e32 v183, 0xffff0000, v195
	v_pk_add_f32 v[108:109], v[108:109], v[182:183]
	global_store_dwordx4 v151, v[110:113], s[70:71]
	global_store_dwordx4 v151, v[106:109], s[70:71] offset:16
	v_mul_f32_e32 v192, v111, v111
	v_mul_f32_e32 v193, v113, v113
	v_mul_f32_e32 v194, v107, v107
	v_mul_f32_e32 v195, v109, v109
	v_fmac_f32_e32 v192, v110, v110
	v_fmac_f32_e32 v193, v112, v112
	v_fmac_f32_e32 v194, v106, v106
	v_fmac_f32_e32 v195, v108, v108
	v_add_f32_e32 v192, v192, v193
	v_add_f32_e32 v192, v192, v194
	v_add_f32_e32 v192, v192, v195
	s_waitcnt vmcnt(18)
	v_lshlrev_b32_e32 v182, 16, v196
	v_and_b32_e32 v183, 0xffff0000, v196
	v_pk_add_f32 v[102:103], v[102:103], v[182:183]
	v_lshlrev_b32_e32 v248, 16, v197
	v_and_b32_e32 v249, 0xffff0000, v197
	v_pk_add_f32 v[104:105], v[104:105], v[248:249]
	v_lshlrev_b32_e32 v138, 16, v198
	v_and_b32_e32 v139, 0xffff0000, v198
	v_pk_add_f32 v[98:99], v[98:99], v[138:139]
	v_lshlrev_b32_e32 v182, 16, v199
	v_and_b32_e32 v183, 0xffff0000, v199
	v_pk_add_f32 v[100:101], v[100:101], v[182:183]
	global_store_dwordx4 v151, v[102:105], s[70:71] offset:512
	global_store_dwordx4 v151, v[98:101], s[70:71] offset:528
	v_mul_f32_e32 v196, v103, v103
	v_mul_f32_e32 v197, v105, v105
	v_mul_f32_e32 v198, v99, v99
	v_mul_f32_e32 v199, v101, v101
	v_fmac_f32_e32 v196, v102, v102
	v_fmac_f32_e32 v197, v104, v104
	v_fmac_f32_e32 v198, v98, v98
	v_fmac_f32_e32 v199, v100, v100
	v_add_f32_e32 v196, v196, v197
	v_add_f32_e32 v196, v196, v198
	v_add_f32_e32 v196, v196, v199
	v_add_f32_e32 v192, v192, v196
	v_add_u32_e32 v151, 0x10000, v151
	s_waitcnt vmcnt(19)
	v_lshlrev_b32_e32 v182, 16, v200
	v_and_b32_e32 v183, 0xffff0000, v200
	v_pk_add_f32 v[94:95], v[94:95], v[182:183]
	v_lshlrev_b32_e32 v248, 16, v201
	v_and_b32_e32 v249, 0xffff0000, v201
	v_pk_add_f32 v[96:97], v[96:97], v[248:249]
	v_lshlrev_b32_e32 v138, 16, v202
	v_and_b32_e32 v139, 0xffff0000, v202
	v_pk_add_f32 v[90:91], v[90:91], v[138:139]
	v_lshlrev_b32_e32 v182, 16, v203
	v_and_b32_e32 v183, 0xffff0000, v203
	v_pk_add_f32 v[92:93], v[92:93], v[182:183]
	global_store_dwordx4 v151, v[94:97], s[70:71]
	global_store_dwordx4 v151, v[90:93], s[70:71] offset:16
	v_mul_f32_e32 v200, v95, v95
	v_mul_f32_e32 v201, v97, v97
	v_mul_f32_e32 v202, v91, v91
	v_mul_f32_e32 v203, v93, v93
	v_fmac_f32_e32 v200, v94, v94
	v_fmac_f32_e32 v201, v96, v96
	v_fmac_f32_e32 v202, v90, v90
	v_fmac_f32_e32 v203, v92, v92
	v_add_f32_e32 v200, v200, v201
	v_add_f32_e32 v200, v200, v202
	v_add_f32_e32 v200, v200, v203
	s_waitcnt vmcnt(20)
	v_lshlrev_b32_e32 v182, 16, v204
	v_and_b32_e32 v183, 0xffff0000, v204
	v_pk_add_f32 v[86:87], v[86:87], v[182:183]
	v_lshlrev_b32_e32 v248, 16, v205
	v_and_b32_e32 v249, 0xffff0000, v205
	v_pk_add_f32 v[88:89], v[88:89], v[248:249]
	v_lshlrev_b32_e32 v138, 16, v206
	v_and_b32_e32 v139, 0xffff0000, v206
	v_pk_add_f32 v[82:83], v[82:83], v[138:139]
	v_lshlrev_b32_e32 v182, 16, v207
	v_and_b32_e32 v183, 0xffff0000, v207
	v_pk_add_f32 v[84:85], v[84:85], v[182:183]
	global_store_dwordx4 v151, v[86:89], s[70:71] offset:512
	global_store_dwordx4 v151, v[82:85], s[70:71] offset:528
	v_mul_f32_e32 v204, v87, v87
	v_mul_f32_e32 v205, v89, v89
	v_mul_f32_e32 v206, v83, v83
	v_mul_f32_e32 v207, v85, v85
	v_fmac_f32_e32 v204, v86, v86
	v_fmac_f32_e32 v205, v88, v88
	v_fmac_f32_e32 v206, v82, v82
	v_fmac_f32_e32 v207, v84, v84
	v_add_f32_e32 v204, v204, v205
	v_add_f32_e32 v204, v204, v206
	v_add_f32_e32 v204, v204, v207
	v_add_f32_e32 v200, v200, v204
	v_add_u32_e32 v151, 0x10000, v151
	s_waitcnt vmcnt(21)
	v_lshlrev_b32_e32 v182, 16, v208
	v_and_b32_e32 v183, 0xffff0000, v208
	v_pk_add_f32 v[78:79], v[78:79], v[182:183]
	v_lshlrev_b32_e32 v248, 16, v209
	v_and_b32_e32 v249, 0xffff0000, v209
	v_pk_add_f32 v[80:81], v[80:81], v[248:249]
	v_lshlrev_b32_e32 v138, 16, v210
	v_and_b32_e32 v139, 0xffff0000, v210
	v_pk_add_f32 v[74:75], v[74:75], v[138:139]
	v_lshlrev_b32_e32 v182, 16, v211
	v_and_b32_e32 v183, 0xffff0000, v211
	v_pk_add_f32 v[76:77], v[76:77], v[182:183]
	global_store_dwordx4 v151, v[78:81], s[70:71]
	global_store_dwordx4 v151, v[74:77], s[70:71] offset:16
	v_mul_f32_e32 v208, v79, v79
	v_mul_f32_e32 v209, v81, v81
	v_mul_f32_e32 v210, v75, v75
	v_mul_f32_e32 v211, v77, v77
	v_fmac_f32_e32 v208, v78, v78
	v_fmac_f32_e32 v209, v80, v80
	v_fmac_f32_e32 v210, v74, v74
	v_fmac_f32_e32 v211, v76, v76
	v_add_f32_e32 v208, v208, v209
	v_add_f32_e32 v208, v208, v210
	v_add_f32_e32 v208, v208, v211
	s_waitcnt vmcnt(22)
	v_lshlrev_b32_e32 v182, 16, v212
	v_and_b32_e32 v183, 0xffff0000, v212
	v_pk_add_f32 v[70:71], v[70:71], v[182:183]
	v_lshlrev_b32_e32 v248, 16, v213
	v_and_b32_e32 v249, 0xffff0000, v213
	v_pk_add_f32 v[72:73], v[72:73], v[248:249]
	v_lshlrev_b32_e32 v138, 16, v214
	v_and_b32_e32 v139, 0xffff0000, v214
	v_pk_add_f32 v[66:67], v[66:67], v[138:139]
	v_lshlrev_b32_e32 v182, 16, v215
	v_and_b32_e32 v183, 0xffff0000, v215
	v_pk_add_f32 v[68:69], v[68:69], v[182:183]
	global_store_dwordx4 v151, v[70:73], s[70:71] offset:512
	global_store_dwordx4 v151, v[66:69], s[70:71] offset:528
	v_mul_f32_e32 v212, v71, v71
	v_mul_f32_e32 v213, v73, v73
	v_mul_f32_e32 v214, v67, v67
	v_mul_f32_e32 v215, v69, v69
	v_fmac_f32_e32 v212, v70, v70
	v_fmac_f32_e32 v213, v72, v72
	v_fmac_f32_e32 v214, v66, v66
	v_fmac_f32_e32 v215, v68, v68
	v_add_f32_e32 v212, v212, v213
	v_add_f32_e32 v212, v212, v214
	v_add_f32_e32 v212, v212, v215
	v_add_f32_e32 v208, v208, v212
	v_add_u32_e32 v151, 0x50000, v151
	s_waitcnt vmcnt(23)
	v_lshlrev_b32_e32 v182, 16, v216
	v_and_b32_e32 v183, 0xffff0000, v216
	v_pk_add_f32 v[60:61], v[60:61], v[182:183]
	v_lshlrev_b32_e32 v248, 16, v217
	v_and_b32_e32 v249, 0xffff0000, v217
	v_pk_add_f32 v[62:63], v[62:63], v[248:249]
	v_lshlrev_b32_e32 v138, 16, v218
	v_and_b32_e32 v139, 0xffff0000, v218
	v_pk_add_f32 v[56:57], v[56:57], v[138:139]
	v_lshlrev_b32_e32 v182, 16, v219
	v_and_b32_e32 v183, 0xffff0000, v219
	v_pk_add_f32 v[58:59], v[58:59], v[182:183]
	global_store_dwordx4 v151, v[60:63], s[70:71]
	global_store_dwordx4 v151, v[56:59], s[70:71] offset:16
	v_mul_f32_e32 v216, v61, v61
	v_mul_f32_e32 v217, v63, v63
	v_mul_f32_e32 v218, v57, v57
	v_mul_f32_e32 v219, v59, v59
	v_fmac_f32_e32 v216, v60, v60
	v_fmac_f32_e32 v217, v62, v62
	v_fmac_f32_e32 v218, v56, v56
	v_fmac_f32_e32 v219, v58, v58
	v_add_f32_e32 v216, v216, v217
	v_add_f32_e32 v216, v216, v218
	v_add_f32_e32 v216, v216, v219
	s_waitcnt vmcnt(24)
	v_lshlrev_b32_e32 v182, 16, v220
	v_and_b32_e32 v183, 0xffff0000, v220
	v_pk_add_f32 v[52:53], v[52:53], v[182:183]
	v_lshlrev_b32_e32 v248, 16, v221
	v_and_b32_e32 v249, 0xffff0000, v221
	v_pk_add_f32 v[54:55], v[54:55], v[248:249]
	v_lshlrev_b32_e32 v138, 16, v222
	v_and_b32_e32 v139, 0xffff0000, v222
	v_pk_add_f32 v[48:49], v[48:49], v[138:139]
	v_lshlrev_b32_e32 v182, 16, v223
	v_and_b32_e32 v183, 0xffff0000, v223
	v_pk_add_f32 v[50:51], v[50:51], v[182:183]
	global_store_dwordx4 v151, v[52:55], s[70:71] offset:512
	global_store_dwordx4 v151, v[48:51], s[70:71] offset:528
	v_mul_f32_e32 v220, v53, v53
	v_mul_f32_e32 v221, v55, v55
	v_mul_f32_e32 v222, v49, v49
	v_mul_f32_e32 v223, v51, v51
	v_fmac_f32_e32 v220, v52, v52
	v_fmac_f32_e32 v221, v54, v54
	v_fmac_f32_e32 v222, v48, v48
	v_fmac_f32_e32 v223, v50, v50
	v_add_f32_e32 v220, v220, v221
	v_add_f32_e32 v220, v220, v222
	v_add_f32_e32 v220, v220, v223
	v_add_f32_e32 v216, v216, v220
	v_add_u32_e32 v151, 0x10000, v151
	s_waitcnt vmcnt(25)
	v_lshlrev_b32_e32 v182, 16, v224
	v_and_b32_e32 v183, 0xffff0000, v224
	v_pk_add_f32 v[44:45], v[44:45], v[182:183]
	v_lshlrev_b32_e32 v248, 16, v225
	v_and_b32_e32 v249, 0xffff0000, v225
	v_pk_add_f32 v[46:47], v[46:47], v[248:249]
	v_lshlrev_b32_e32 v138, 16, v226
	v_and_b32_e32 v139, 0xffff0000, v226
	v_pk_add_f32 v[40:41], v[40:41], v[138:139]
	v_lshlrev_b32_e32 v182, 16, v227
	v_and_b32_e32 v183, 0xffff0000, v227
	v_pk_add_f32 v[42:43], v[42:43], v[182:183]
	global_store_dwordx4 v151, v[44:47], s[70:71]
	global_store_dwordx4 v151, v[40:43], s[70:71] offset:16
	v_mul_f32_e32 v224, v45, v45
	v_mul_f32_e32 v225, v47, v47
	v_mul_f32_e32 v226, v41, v41
	v_mul_f32_e32 v227, v43, v43
	v_fmac_f32_e32 v224, v44, v44
	v_fmac_f32_e32 v225, v46, v46
	v_fmac_f32_e32 v226, v40, v40
	v_fmac_f32_e32 v227, v42, v42
	v_add_f32_e32 v224, v224, v225
	v_add_f32_e32 v224, v224, v226
	v_add_f32_e32 v224, v224, v227
	s_waitcnt vmcnt(26)
	v_lshlrev_b32_e32 v182, 16, v228
	v_and_b32_e32 v183, 0xffff0000, v228
	v_pk_add_f32 v[36:37], v[36:37], v[182:183]
	v_lshlrev_b32_e32 v248, 16, v229
	v_and_b32_e32 v249, 0xffff0000, v229
	v_pk_add_f32 v[38:39], v[38:39], v[248:249]
	v_lshlrev_b32_e32 v138, 16, v230
	v_and_b32_e32 v139, 0xffff0000, v230
	v_pk_add_f32 v[32:33], v[32:33], v[138:139]
	v_lshlrev_b32_e32 v182, 16, v231
	v_and_b32_e32 v183, 0xffff0000, v231
	v_pk_add_f32 v[34:35], v[34:35], v[182:183]
	global_store_dwordx4 v151, v[36:39], s[70:71] offset:512
	global_store_dwordx4 v151, v[32:35], s[70:71] offset:528
	v_mul_f32_e32 v228, v37, v37
	v_mul_f32_e32 v229, v39, v39
	v_mul_f32_e32 v230, v33, v33
	v_mul_f32_e32 v231, v35, v35
	v_fmac_f32_e32 v228, v36, v36
	v_fmac_f32_e32 v229, v38, v38
	v_fmac_f32_e32 v230, v32, v32
	v_fmac_f32_e32 v231, v34, v34
	v_add_f32_e32 v228, v228, v229
	v_add_f32_e32 v228, v228, v230
	v_add_f32_e32 v228, v228, v231
	v_add_f32_e32 v224, v224, v228
	v_add_u32_e32 v151, 0x10000, v151
	s_waitcnt vmcnt(27)
	v_lshlrev_b32_e32 v182, 16, v232
	v_and_b32_e32 v183, 0xffff0000, v232
	v_pk_add_f32 v[28:29], v[28:29], v[182:183]
	v_lshlrev_b32_e32 v248, 16, v233
	v_and_b32_e32 v249, 0xffff0000, v233
	v_pk_add_f32 v[30:31], v[30:31], v[248:249]
	v_lshlrev_b32_e32 v138, 16, v234
	v_and_b32_e32 v139, 0xffff0000, v234
	v_pk_add_f32 v[24:25], v[24:25], v[138:139]
	v_lshlrev_b32_e32 v182, 16, v235
	v_and_b32_e32 v183, 0xffff0000, v235
	v_pk_add_f32 v[26:27], v[26:27], v[182:183]
	global_store_dwordx4 v151, v[28:31], s[70:71]
	global_store_dwordx4 v151, v[24:27], s[70:71] offset:16
	v_mul_f32_e32 v232, v29, v29
	v_mul_f32_e32 v233, v31, v31
	v_mul_f32_e32 v234, v25, v25
	v_mul_f32_e32 v235, v27, v27
	v_fmac_f32_e32 v232, v28, v28
	v_fmac_f32_e32 v233, v30, v30
	v_fmac_f32_e32 v234, v24, v24
	v_fmac_f32_e32 v235, v26, v26
	v_add_f32_e32 v232, v232, v233
	v_add_f32_e32 v232, v232, v234
	v_add_f32_e32 v232, v232, v235
	s_waitcnt vmcnt(28)
	v_lshlrev_b32_e32 v182, 16, v236
	v_and_b32_e32 v183, 0xffff0000, v236
	v_pk_add_f32 v[20:21], v[20:21], v[182:183]
	v_lshlrev_b32_e32 v248, 16, v237
	v_and_b32_e32 v249, 0xffff0000, v237
	v_pk_add_f32 v[22:23], v[22:23], v[248:249]
	v_lshlrev_b32_e32 v138, 16, v238
	v_and_b32_e32 v139, 0xffff0000, v238
	v_pk_add_f32 v[16:17], v[16:17], v[138:139]
	v_lshlrev_b32_e32 v182, 16, v239
	v_and_b32_e32 v183, 0xffff0000, v239
	v_pk_add_f32 v[18:19], v[18:19], v[182:183]
	global_store_dwordx4 v151, v[20:23], s[70:71] offset:512
	global_store_dwordx4 v151, v[16:19], s[70:71] offset:528
	v_mul_f32_e32 v236, v21, v21
	v_mul_f32_e32 v237, v23, v23
	v_mul_f32_e32 v238, v17, v17
	v_mul_f32_e32 v239, v19, v19
	v_fmac_f32_e32 v236, v20, v20
	v_fmac_f32_e32 v237, v22, v22
	v_fmac_f32_e32 v238, v16, v16
	v_fmac_f32_e32 v239, v18, v18
	v_add_f32_e32 v236, v236, v237
	v_add_f32_e32 v236, v236, v238
	v_add_f32_e32 v236, v236, v239
	v_add_f32_e32 v232, v232, v236
	v_add_u32_e32 v151, 0x10000, v151
	s_waitcnt vmcnt(29)
	v_lshlrev_b32_e32 v182, 16, v240
	v_and_b32_e32 v183, 0xffff0000, v240
	v_pk_add_f32 v[12:13], v[12:13], v[182:183]
	v_lshlrev_b32_e32 v248, 16, v241
	v_and_b32_e32 v249, 0xffff0000, v241
	v_pk_add_f32 v[14:15], v[14:15], v[248:249]
	v_lshlrev_b32_e32 v138, 16, v242
	v_and_b32_e32 v139, 0xffff0000, v242
	v_pk_add_f32 v[8:9], v[8:9], v[138:139]
	v_lshlrev_b32_e32 v182, 16, v243
	v_and_b32_e32 v183, 0xffff0000, v243
	v_pk_add_f32 v[10:11], v[10:11], v[182:183]
	global_store_dwordx4 v151, v[12:15], s[70:71]
	global_store_dwordx4 v151, v[8:11], s[70:71] offset:16
	v_mul_f32_e32 v240, v13, v13
	v_mul_f32_e32 v241, v15, v15
	v_mul_f32_e32 v242, v9, v9
	v_mul_f32_e32 v243, v11, v11
	v_fmac_f32_e32 v240, v12, v12
	v_fmac_f32_e32 v241, v14, v14
	v_fmac_f32_e32 v242, v8, v8
	v_fmac_f32_e32 v243, v10, v10
	v_add_f32_e32 v240, v240, v241
	v_add_f32_e32 v240, v240, v242
	v_add_f32_e32 v240, v240, v243
	s_waitcnt vmcnt(30)
	v_lshlrev_b32_e32 v182, 16, v244
	v_and_b32_e32 v183, 0xffff0000, v244
	v_pk_add_f32 v[4:5], v[4:5], v[182:183]
	v_lshlrev_b32_e32 v248, 16, v245
	v_and_b32_e32 v249, 0xffff0000, v245
	v_pk_add_f32 v[6:7], v[6:7], v[248:249]
	v_lshlrev_b32_e32 v138, 16, v246
	v_and_b32_e32 v139, 0xffff0000, v246
	v_pk_add_f32 v[0:1], v[0:1], v[138:139]
	v_lshlrev_b32_e32 v182, 16, v247
	v_and_b32_e32 v183, 0xffff0000, v247
	v_pk_add_f32 v[2:3], v[2:3], v[182:183]
	global_store_dwordx4 v151, v[4:7], s[70:71] offset:512
	global_store_dwordx4 v151, v[0:3], s[70:71] offset:528
	v_mul_f32_e32 v244, v5, v5
	v_mul_f32_e32 v245, v7, v7
	v_mul_f32_e32 v246, v1, v1
	v_mul_f32_e32 v247, v3, v3
	v_fmac_f32_e32 v244, v4, v4
	v_fmac_f32_e32 v245, v6, v6
	v_fmac_f32_e32 v246, v0, v0
	v_fmac_f32_e32 v247, v2, v2
	v_add_f32_e32 v244, v244, v245
	v_add_f32_e32 v244, v244, v246
	v_add_f32_e32 v244, v244, v247
	v_add_f32_e32 v240, v240, v244
	v_mov_b32_e32 v175, v184
	s_nop 1
	v_permlane16_swap_b32_e32 v175, v184
	v_add_f32_e32 v184, v175, v184
	v_mov_b32_e32 v175, v192
	s_nop 1
	v_permlane16_swap_b32_e32 v175, v192
	v_add_f32_e32 v192, v175, v192
	v_mov_b32_e32 v175, v200
	s_nop 1
	v_permlane16_swap_b32_e32 v175, v200
	v_add_f32_e32 v200, v175, v200
	v_mov_b32_e32 v175, v208
	s_nop 1
	v_permlane16_swap_b32_e32 v175, v208
	v_add_f32_e32 v208, v175, v208
	v_mov_b32_e32 v175, v216
	s_nop 1
	v_permlane16_swap_b32_e32 v175, v216
	v_add_f32_e32 v216, v175, v216
	v_mov_b32_e32 v175, v224
	s_nop 1
	v_permlane16_swap_b32_e32 v175, v224
	v_add_f32_e32 v224, v175, v224
	v_mov_b32_e32 v175, v232
	s_nop 1
	v_permlane16_swap_b32_e32 v175, v232
	v_add_f32_e32 v232, v175, v232
	v_mov_b32_e32 v175, v240
	s_nop 1
	v_permlane16_swap_b32_e32 v175, v240
	v_add_f32_e32 v240, v175, v240
	v_mov_b32_e32 v175, v184
	s_nop 1
	v_permlane32_swap_b32_e32 v175, v184
	v_add_f32_e32 v184, v175, v184
	v_mov_b32_e32 v175, v192
	s_nop 1
	v_permlane32_swap_b32_e32 v175, v192
	v_add_f32_e32 v192, v175, v192
	v_mov_b32_e32 v175, v200
	s_nop 1
	v_permlane32_swap_b32_e32 v175, v200
	v_add_f32_e32 v200, v175, v200
	v_mov_b32_e32 v175, v208
	s_nop 1
	v_permlane32_swap_b32_e32 v175, v208
	v_add_f32_e32 v208, v175, v208
	v_mov_b32_e32 v175, v216
	s_nop 1
	v_permlane32_swap_b32_e32 v175, v216
	v_add_f32_e32 v216, v175, v216
	v_mov_b32_e32 v175, v224
	s_nop 1
	v_permlane32_swap_b32_e32 v175, v224
	v_add_f32_e32 v224, v175, v224
	v_mov_b32_e32 v175, v232
	s_nop 1
	v_permlane32_swap_b32_e32 v175, v232
	v_add_f32_e32 v232, v175, v232
	v_mov_b32_e32 v175, v240
	s_nop 1
	v_permlane32_swap_b32_e32 v175, v240
	v_add_f32_e32 v240, v175, v240
	s_add_u32 s74, s28, s54
	s_addc_u32 s75, s29, 0
	s_and_saveexec_b64 s[4:5], s[38:39]
	s_nop 1
	global_store_dword v149, v184, s[74:75]
	v_add_u32_e32 v149, 0x400, v149
	global_store_dword v149, v192, s[74:75]
	v_add_u32_e32 v149, 0x400, v149
	global_store_dword v149, v200, s[74:75]
	v_add_u32_e32 v149, 0x400, v149
	global_store_dword v149, v208, s[74:75]
	v_add_u32_e32 v149, 0x1400, v149
	global_store_dword v149, v216, s[74:75]
	v_add_u32_e32 v149, 0x400, v149
	global_store_dword v149, v224, s[74:75]
	v_add_u32_e32 v149, 0x400, v149
	global_store_dword v149, v232, s[74:75]
	v_add_u32_e32 v149, 0x400, v149
	global_store_dword v149, v240, s[74:75]
	s_or_b64 exec, exec, s[4:5]
	s_mov_b32 s54, s55
	s_mov_b32 s55, 0
	s_lshl_b32 s76, s24, 2
	v_readlane_b32 s74, v255, 32
	v_readlane_b32 s75, v255, 33
	s_movk_i32 s78, 0xf800
	v_readlane_b32 s70, v255, 26
	v_readlane_b32 s71, v255, 27
	s_branch .Lffn2_done
	v_lshl_add_u32 v150, s29, 8, v172
	s_lshl_b32 s4, s28, 8
	s_ashr_i32 s5, s4, 31
	v_ashrrev_i32_e32 v151, 31, v150
	v_mov_b32_e32 v149, s5
	v_or_b32_e32 v148, s4, v142
	v_lshlrev_b64 v[138:139], 10, v[150:151]
	v_lshl_add_u64 v[138:139], v[138:139], 0, v[148:149]
	v_lshl_add_u64 v[182:183], v[138:139], 1, s[30:31]
	global_load_dwordx4 v[184:187], v[182:183], off
	v_lshl_add_u64 v[138:139], v[138:139], 2, s[8:9]
	s_lshl_b32 s54, s28, 2
	s_ashr_i32 s55, s54, 31
	s_waitcnt vmcnt(0)
	v_lshlrev_b32_e32 v188, 16, v184
	v_and_b32_e32 v189, 0xffff0000, v184
	v_lshlrev_b32_e32 v184, 16, v185
	v_and_b32_e32 v185, 0xffff0000, v185
	v_lshlrev_b32_e32 v190, 16, v186
	v_and_b32_e32 v191, 0xffff0000, v186
	v_lshlrev_b32_e32 v186, 16, v187
	v_and_b32_e32 v187, 0xffff0000, v187
	v_pk_add_f32 v[128:129], v[128:129], v[184:185]
	v_pk_add_f32 v[126:127], v[126:127], v[188:189]
	v_pk_add_f32 v[186:187], v[124:125], v[186:187]
	v_pk_add_f32 v[184:185], v[122:123], v[190:191]
	global_store_dwordx4 v[138:139], v[126:129], off
	global_store_dwordx4 v[138:139], v[184:187], off offset:16
	global_load_dwordx4 v[188:191], v[182:183], off offset:256
	v_mul_f32_e32 v124, v127, v127
	v_mul_f32_e32 v125, v129, v129
	v_mul_f32_e32 v127, v185, v185
	v_fmac_f32_e32 v124, v126, v126
	v_fmac_f32_e32 v125, v128, v128
	v_mul_f32_e32 v129, v187, v187
	v_fmac_f32_e32 v127, v184, v184
	v_add_f32_e32 v124, v124, v125
	v_fmac_f32_e32 v129, v186, v186
	v_add_f32_e32 v124, v127, v124
	v_add_f32_e32 v175, v129, v124
	v_and_b32_e32 v123, 64, v178
	v_xor_b32_e32 v122, 16, v178
	v_add_u32_e32 v123, 64, v123
	v_cmp_lt_i32_e32 vcc, v122, v123
	s_waitcnt vmcnt(0)
	v_lshlrev_b32_e32 v124, 16, v188
	v_and_b32_e32 v125, 0xffff0000, v188
	v_lshlrev_b32_e32 v126, 16, v189
	v_and_b32_e32 v127, 0xffff0000, v189
	v_lshlrev_b32_e32 v128, 16, v190
	v_and_b32_e32 v129, 0xffff0000, v190
	v_pk_add_f32 v[120:121], v[120:121], v[126:127]
	v_pk_add_f32 v[118:119], v[118:119], v[124:125]
	v_lshlrev_b32_e32 v182, 16, v191
	v_and_b32_e32 v183, 0xffff0000, v191
	v_pk_add_f32 v[124:125], v[114:115], v[128:129]
	v_mul_f32_e32 v114, v119, v119
	v_mul_f32_e32 v115, v121, v121
	v_pk_add_f32 v[126:127], v[116:117], v[182:183]
	v_mul_f32_e32 v116, v125, v125
	v_fmac_f32_e32 v114, v118, v118
	v_fmac_f32_e32 v115, v120, v120
	v_mul_f32_e32 v117, v127, v127
	v_fmac_f32_e32 v116, v124, v124
	v_add_f32_e32 v114, v114, v115
	v_add_f32_e32 v114, v116, v114
	v_fmac_f32_e32 v117, v126, v126
	v_cndmask_b32_e32 v122, v178, v122, vcc
	v_add_f32_e32 v114, v117, v114
	v_lshlrev_b32_e32 v122, 2, v122
	v_add_f32_e32 v114, v175, v114
	ds_bpermute_b32 v115, v122, v114
	v_xor_b32_e32 v116, 32, v178
	v_cmp_lt_i32_e32 vcc, v116, v123
	global_store_dwordx4 v[138:139], v[118:121], off offset:512
	global_store_dwordx4 v[138:139], v[124:127], off offset:528
	v_cndmask_b32_e32 v116, v178, v116, vcc
	v_lshlrev_b32_e32 v116, 2, v116
	s_waitcnt lgkmcnt(0)
	v_add_f32_e32 v114, v114, v115
	ds_bpermute_b32 v115, v116, v114
	s_and_saveexec_b64 s[4:5], s[38:39]
	s_movk_i32 s78, 0xf800
	s_cbranch_execz .LBB0_151
	v_readlane_b32 s28, v250, 40
	v_lshlrev_b64 v[118:119], 6, v[150:151]
	v_readlane_b32 s29, v250, 41
	s_lshl_b32 s76, s24, 2
	s_waitcnt lgkmcnt(0)
	v_add_f32_e32 v114, v114, v115
	v_lshl_add_u64 v[118:119], s[28:29], 0, v[118:119]
	v_lshl_add_u64 v[118:119], s[54:55], 2, v[118:119]
	v_lshl_add_u64 v[118:119], v[118:119], 0, s[76:77]
	global_store_dword v[118:119], v114, off

.Lffn2_done:
	s_andn2_b64 vcc, exec, s[40:41]
	s_mov_b64 s[4:5], -1
	s_cbranch_vccnz .LBB0_138
	s_andn2_b64 vcc, exec, s[0:1]
	s_cbranch_vccnz .LBB0_137
	s_barrier
	s_branch .LBB0_137

.LBB0_186:
	v_readlane_b32 s4, v250, 25
	v_mbcnt_lo_u32_b32 v138, -1, 0
	v_mbcnt_hi_u32_b32 v138, -1, v138
	s_nop 1
	s_lshr_b32 s5, s4, 8
	s_bfe_u32 s4, s4, 0x20006
	v_and_b32_e32 v139, 15, v138
	v_lshrrev_b32_e32 v148, 4, v138
	s_lshl_b32 s70, s29, 8
	s_lshl_b32 s5, s5, 6
	s_add_u32 s5, s5, s70
	v_add_u32_e32 v139, s5, v139
	v_lshlrev_b32_e32 v149, 6, v139
	v_lshlrev_b32_e32 v150, 12, v139
	v_lshl_add_u32 v150, v148, 5, v150
	s_lshl_b32 s71, s4, 7
	v_add_u32_e32 v150, s71, v150
	v_lshlrev_b32_e32 v151, 11, v139
	v_lshl_add_u32 v151, v148, 4, v151
	s_lshl_b32 s71, s4, 6
	v_add_u32_e32 v151, s71, v151
	s_lshl_b32 s76, s28, 9
	s_add_u32 s74, s30, s76
	s_addc_u32 s75, s31, 0
	s_lshl_b32 s76, s28, 10
	s_add_u32 s70, s36, s76
	s_addc_u32 s71, s37, 0
	s_lshl_b32 s55, s28, 2
	s_lshl_b32 s54, s28, 4
	s_lshl_b32 s76, s4, 2
	s_add_u32 s54, s54, s76
	v_readlane_b32 s28, v250, 23
	v_readlane_b32 s29, v250, 24
	global_load_dwordx4 v[184:187], v150, s[70:71]
	global_load_dwordx4 v[188:191], v150, s[70:71] offset:16
	global_load_dwordx4 v[192:195], v150, s[70:71] offset:512
	global_load_dwordx4 v[196:199], v150, s[70:71] offset:528
	v_add_u32_e32 v150, 0x10000, v150
	global_load_dwordx4 v[200:203], v150, s[70:71]
	global_load_dwordx4 v[204:207], v150, s[70:71] offset:16
	global_load_dwordx4 v[208:211], v150, s[70:71] offset:512
	global_load_dwordx4 v[212:215], v150, s[70:71] offset:528
	v_add_u32_e32 v150, 0x10000, v150
	global_load_dwordx4 v[216:219], v150, s[70:71]
	global_load_dwordx4 v[220:223], v150, s[70:71] offset:16
	global_load_dwordx4 v[224:227], v150, s[70:71] offset:512
	global_load_dwordx4 v[228:231], v150, s[70:71] offset:528
	v_add_u32_e32 v150, 0x10000, v150
	global_load_dwordx4 v[162:165], v150, s[70:71]
	global_load_dwordx4 v[166:169], v150, s[70:71] offset:16
	global_load_dwordx4 v[170:173], v150, s[70:71] offset:512
	global_load_dwordx4 v[152:155], v150, s[70:71] offset:528
	v_add_u32_e32 v150, 0x50000, v150
	s_waitcnt vmcnt(14)
	v_pk_add_f32 v[126:127], v[126:127], v[184:185]
	v_pk_add_f32 v[128:129], v[128:129], v[186:187]
	v_pk_add_f32 v[122:123], v[122:123], v[188:189]
	v_pk_add_f32 v[124:125], v[124:125], v[190:191]
	v_cvt_pk_bf16_f32 v126, v126, v127
	v_cvt_pk_bf16_f32 v127, v128, v129
	v_cvt_pk_bf16_f32 v128, v122, v123
	v_cvt_pk_bf16_f32 v129, v124, v125
	global_store_dwordx4 v151, v[126:129], s[74:75]
	v_lshlrev_b32_e32 v184, 16, v126
	v_lshlrev_b32_e32 v185, 16, v127
	v_lshlrev_b32_e32 v186, 16, v128
	v_lshlrev_b32_e32 v187, 16, v129
	v_and_b32_e32 v122, 0xffff0000, v126
	v_and_b32_e32 v123, 0xffff0000, v127
	v_and_b32_e32 v124, 0xffff0000, v128
	v_and_b32_e32 v125, 0xffff0000, v129
	v_mul_f32_e32 v122, v122, v122
	v_mul_f32_e32 v123, v123, v123
	v_mul_f32_e32 v124, v124, v124
	v_mul_f32_e32 v125, v125, v125
	v_fmac_f32_e32 v122, v184, v184
	v_fmac_f32_e32 v123, v185, v185
	v_fmac_f32_e32 v124, v186, v186
	v_fmac_f32_e32 v125, v187, v187
	v_add_f32_e32 v122, v122, v123
	v_add_f32_e32 v122, v122, v124
	v_add_f32_e32 v122, v122, v125
	s_waitcnt vmcnt(13)
	v_pk_add_f32 v[118:119], v[118:119], v[192:193]
	v_pk_add_f32 v[120:121], v[120:121], v[194:195]
	v_pk_add_f32 v[114:115], v[114:115], v[196:197]
	v_pk_add_f32 v[116:117], v[116:117], v[198:199]
	v_cvt_pk_bf16_f32 v118, v118, v119
	v_cvt_pk_bf16_f32 v119, v120, v121
	v_cvt_pk_bf16_f32 v120, v114, v115
	v_cvt_pk_bf16_f32 v121, v116, v117
	global_store_dwordx4 v151, v[118:121], s[74:75] offset:256
	v_lshlrev_b32_e32 v192, 16, v118
	v_lshlrev_b32_e32 v193, 16, v119
	v_lshlrev_b32_e32 v194, 16, v120
	v_lshlrev_b32_e32 v195, 16, v121
	v_and_b32_e32 v114, 0xffff0000, v118
	v_and_b32_e32 v115, 0xffff0000, v119
	v_and_b32_e32 v116, 0xffff0000, v120
	v_and_b32_e32 v117, 0xffff0000, v121
	v_mul_f32_e32 v114, v114, v114
	v_mul_f32_e32 v115, v115, v115
	v_mul_f32_e32 v116, v116, v116
	v_mul_f32_e32 v117, v117, v117
	v_fmac_f32_e32 v114, v192, v192
	v_fmac_f32_e32 v115, v193, v193
	v_fmac_f32_e32 v116, v194, v194
	v_fmac_f32_e32 v117, v195, v195
	v_add_f32_e32 v114, v114, v115
	v_add_f32_e32 v114, v114, v116
	v_add_f32_e32 v114, v114, v117
	v_add_f32_e32 v122, v122, v114
	v_add_u32_e32 v151, 0x8000, v151
	global_load_dwordx4 v[184:187], v150, s[70:71]
	global_load_dwordx4 v[188:191], v150, s[70:71] offset:16
	global_load_dwordx4 v[192:195], v150, s[70:71] offset:512
	global_load_dwordx4 v[196:199], v150, s[70:71] offset:528
	v_add_u32_e32 v150, 0x10000, v150
	s_waitcnt vmcnt(16)
	v_pk_add_f32 v[110:111], v[110:111], v[200:201]
	v_pk_add_f32 v[112:113], v[112:113], v[202:203]
	v_pk_add_f32 v[106:107], v[106:107], v[204:205]
	v_pk_add_f32 v[108:109], v[108:109], v[206:207]
	v_cvt_pk_bf16_f32 v110, v110, v111
	v_cvt_pk_bf16_f32 v111, v112, v113
	v_cvt_pk_bf16_f32 v112, v106, v107
	v_cvt_pk_bf16_f32 v113, v108, v109
	global_store_dwordx4 v151, v[110:113], s[74:75]
	v_lshlrev_b32_e32 v200, 16, v110
	v_lshlrev_b32_e32 v201, 16, v111
	v_lshlrev_b32_e32 v202, 16, v112
	v_lshlrev_b32_e32 v203, 16, v113
	v_and_b32_e32 v106, 0xffff0000, v110
	v_and_b32_e32 v107, 0xffff0000, v111
	v_and_b32_e32 v108, 0xffff0000, v112
	v_and_b32_e32 v109, 0xffff0000, v113
	v_mul_f32_e32 v106, v106, v106
	v_mul_f32_e32 v107, v107, v107
	v_mul_f32_e32 v108, v108, v108
	v_mul_f32_e32 v109, v109, v109
	v_fmac_f32_e32 v106, v200, v200
	v_fmac_f32_e32 v107, v201, v201
	v_fmac_f32_e32 v108, v202, v202
	v_fmac_f32_e32 v109, v203, v203
	v_add_f32_e32 v106, v106, v107
	v_add_f32_e32 v106, v106, v108
	v_add_f32_e32 v106, v106, v109
	s_waitcnt vmcnt(15)
	v_pk_add_f32 v[102:103], v[102:103], v[208:209]
	v_pk_add_f32 v[104:105], v[104:105], v[210:211]
	v_pk_add_f32 v[98:99], v[98:99], v[212:213]
	v_pk_add_f32 v[100:101], v[100:101], v[214:215]
	v_cvt_pk_bf16_f32 v102, v102, v103
	v_cvt_pk_bf16_f32 v103, v104, v105
	v_cvt_pk_bf16_f32 v104, v98, v99
	v_cvt_pk_bf16_f32 v105, v100, v101
	global_store_dwordx4 v151, v[102:105], s[74:75] offset:256
	v_lshlrev_b32_e32 v208, 16, v102
	v_lshlrev_b32_e32 v209, 16, v103
	v_lshlrev_b32_e32 v210, 16, v104
	v_lshlrev_b32_e32 v211, 16, v105
	v_and_b32_e32 v98, 0xffff0000, v102
	v_and_b32_e32 v99, 0xffff0000, v103
	v_and_b32_e32 v100, 0xffff0000, v104
	v_and_b32_e32 v101, 0xffff0000, v105
	v_mul_f32_e32 v98, v98, v98
	v_mul_f32_e32 v99, v99, v99
	v_mul_f32_e32 v100, v100, v100
	v_mul_f32_e32 v101, v101, v101
	v_fmac_f32_e32 v98, v208, v208
	v_fmac_f32_e32 v99, v209, v209
	v_fmac_f32_e32 v100, v210, v210
	v_fmac_f32_e32 v101, v211, v211
	v_add_f32_e32 v98, v98, v99
	v_add_f32_e32 v98, v98, v100
	v_add_f32_e32 v98, v98, v101
	v_add_f32_e32 v106, v106, v98
	v_add_u32_e32 v151, 0x8000, v151
	global_load_dwordx4 v[200:203], v150, s[70:71]
	global_load_dwordx4 v[204:207], v150, s[70:71] offset:16
	global_load_dwordx4 v[208:211], v150, s[70:71] offset:512
	global_load_dwordx4 v[212:215], v150, s[70:71] offset:528
	v_add_u32_e32 v150, 0x10000, v150
	s_waitcnt vmcnt(18)
	v_pk_add_f32 v[94:95], v[94:95], v[216:217]
	v_pk_add_f32 v[96:97], v[96:97], v[218:219]
	v_pk_add_f32 v[90:91], v[90:91], v[220:221]
	v_pk_add_f32 v[92:93], v[92:93], v[222:223]
	v_cvt_pk_bf16_f32 v94, v94, v95
	v_cvt_pk_bf16_f32 v95, v96, v97
	v_cvt_pk_bf16_f32 v96, v90, v91
	v_cvt_pk_bf16_f32 v97, v92, v93
	global_store_dwordx4 v151, v[94:97], s[74:75]
	v_lshlrev_b32_e32 v216, 16, v94
	v_lshlrev_b32_e32 v217, 16, v95
	v_lshlrev_b32_e32 v218, 16, v96
	v_lshlrev_b32_e32 v219, 16, v97
	v_and_b32_e32 v90, 0xffff0000, v94
	v_and_b32_e32 v91, 0xffff0000, v95
	v_and_b32_e32 v92, 0xffff0000, v96
	v_and_b32_e32 v93, 0xffff0000, v97
	v_mul_f32_e32 v90, v90, v90
	v_mul_f32_e32 v91, v91, v91
	v_mul_f32_e32 v92, v92, v92
	v_mul_f32_e32 v93, v93, v93
	v_fmac_f32_e32 v90, v216, v216
	v_fmac_f32_e32 v91, v217, v217
	v_fmac_f32_e32 v92, v218, v218
	v_fmac_f32_e32 v93, v219, v219
	v_add_f32_e32 v90, v90, v91
	v_add_f32_e32 v90, v90, v92
	v_add_f32_e32 v90, v90, v93
	s_waitcnt vmcnt(17)
	v_pk_add_f32 v[86:87], v[86:87], v[224:225]
	v_pk_add_f32 v[88:89], v[88:89], v[226:227]
	v_pk_add_f32 v[82:83], v[82:83], v[228:229]
	v_pk_add_f32 v[84:85], v[84:85], v[230:231]
	v_cvt_pk_bf16_f32 v86, v86, v87
	v_cvt_pk_bf16_f32 v87, v88, v89
	v_cvt_pk_bf16_f32 v88, v82, v83
	v_cvt_pk_bf16_f32 v89, v84, v85
	global_store_dwordx4 v151, v[86:89], s[74:75] offset:256
	v_lshlrev_b32_e32 v224, 16, v86
	v_lshlrev_b32_e32 v225, 16, v87
	v_lshlrev_b32_e32 v226, 16, v88
	v_lshlrev_b32_e32 v227, 16, v89
	v_and_b32_e32 v82, 0xffff0000, v86
	v_and_b32_e32 v83, 0xffff0000, v87
	v_and_b32_e32 v84, 0xffff0000, v88
	v_and_b32_e32 v85, 0xffff0000, v89
	v_mul_f32_e32 v82, v82, v82
	v_mul_f32_e32 v83, v83, v83
	v_mul_f32_e32 v84, v84, v84
	v_mul_f32_e32 v85, v85, v85
	v_fmac_f32_e32 v82, v224, v224
	v_fmac_f32_e32 v83, v225, v225
	v_fmac_f32_e32 v84, v226, v226
	v_fmac_f32_e32 v85, v227, v227
	v_add_f32_e32 v82, v82, v83
	v_add_f32_e32 v82, v82, v84
	v_add_f32_e32 v82, v82, v85
	v_add_f32_e32 v90, v90, v82
	v_add_u32_e32 v151, 0x8000, v151
	global_load_dwordx4 v[216:219], v150, s[70:71]
	global_load_dwordx4 v[220:223], v150, s[70:71] offset:16
	global_load_dwordx4 v[224:227], v150, s[70:71] offset:512
	global_load_dwordx4 v[228:231], v150, s[70:71] offset:528
	v_add_u32_e32 v150, 0x10000, v150
	s_waitcnt vmcnt(20)
	v_pk_add_f32 v[78:79], v[78:79], v[162:163]
	v_pk_add_f32 v[80:81], v[80:81], v[164:165]
	v_pk_add_f32 v[74:75], v[74:75], v[166:167]
	v_pk_add_f32 v[76:77], v[76:77], v[168:169]
	v_cvt_pk_bf16_f32 v78, v78, v79
	v_cvt_pk_bf16_f32 v79, v80, v81
	v_cvt_pk_bf16_f32 v80, v74, v75
	v_cvt_pk_bf16_f32 v81, v76, v77
	global_store_dwordx4 v151, v[78:81], s[74:75]
	v_lshlrev_b32_e32 v162, 16, v78
	v_lshlrev_b32_e32 v163, 16, v79
	v_lshlrev_b32_e32 v164, 16, v80
	v_lshlrev_b32_e32 v165, 16, v81
	v_and_b32_e32 v74, 0xffff0000, v78
	v_and_b32_e32 v75, 0xffff0000, v79
	v_and_b32_e32 v76, 0xffff0000, v80
	v_and_b32_e32 v77, 0xffff0000, v81
	v_mul_f32_e32 v74, v74, v74
	v_mul_f32_e32 v75, v75, v75
	v_mul_f32_e32 v76, v76, v76
	v_mul_f32_e32 v77, v77, v77
	v_fmac_f32_e32 v74, v162, v162
	v_fmac_f32_e32 v75, v163, v163
	v_fmac_f32_e32 v76, v164, v164
	v_fmac_f32_e32 v77, v165, v165
	v_add_f32_e32 v74, v74, v75
	v_add_f32_e32 v74, v74, v76
	v_add_f32_e32 v74, v74, v77
	s_waitcnt vmcnt(19)
	v_pk_add_f32 v[70:71], v[70:71], v[170:171]
	v_pk_add_f32 v[72:73], v[72:73], v[172:173]
	v_pk_add_f32 v[66:67], v[66:67], v[152:153]
	v_pk_add_f32 v[68:69], v[68:69], v[154:155]
	v_cvt_pk_bf16_f32 v70, v70, v71
	v_cvt_pk_bf16_f32 v71, v72, v73
	v_cvt_pk_bf16_f32 v72, v66, v67
	v_cvt_pk_bf16_f32 v73, v68, v69
	global_store_dwordx4 v151, v[70:73], s[74:75] offset:256
	v_lshlrev_b32_e32 v170, 16, v70
	v_lshlrev_b32_e32 v171, 16, v71
	v_lshlrev_b32_e32 v172, 16, v72
	v_lshlrev_b32_e32 v173, 16, v73
	v_and_b32_e32 v66, 0xffff0000, v70
	v_and_b32_e32 v67, 0xffff0000, v71
	v_and_b32_e32 v68, 0xffff0000, v72
	v_and_b32_e32 v69, 0xffff0000, v73
	v_mul_f32_e32 v66, v66, v66
	v_mul_f32_e32 v67, v67, v67
	v_mul_f32_e32 v68, v68, v68
	v_mul_f32_e32 v69, v69, v69
	v_fmac_f32_e32 v66, v170, v170
	v_fmac_f32_e32 v67, v171, v171
	v_fmac_f32_e32 v68, v172, v172
	v_fmac_f32_e32 v69, v173, v173
	v_add_f32_e32 v66, v66, v67
	v_add_f32_e32 v66, v66, v68
	v_add_f32_e32 v66, v66, v69
	v_add_f32_e32 v74, v74, v66
	v_add_u32_e32 v151, 0x28000, v151
	global_load_dwordx4 v[162:165], v150, s[70:71]
	global_load_dwordx4 v[166:169], v150, s[70:71] offset:16
	global_load_dwordx4 v[170:173], v150, s[70:71] offset:512
	global_load_dwordx4 v[152:155], v150, s[70:71] offset:528
	s_waitcnt vmcnt(20)
	v_pk_add_f32 v[60:61], v[60:61], v[184:185]
	v_pk_add_f32 v[62:63], v[62:63], v[186:187]
	v_pk_add_f32 v[56:57], v[56:57], v[188:189]
	v_pk_add_f32 v[58:59], v[58:59], v[190:191]
	v_cvt_pk_bf16_f32 v60, v60, v61
	v_cvt_pk_bf16_f32 v61, v62, v63
	v_cvt_pk_bf16_f32 v62, v56, v57
	v_cvt_pk_bf16_f32 v63, v58, v59
	global_store_dwordx4 v151, v[60:63], s[74:75]
	v_lshlrev_b32_e32 v184, 16, v60
	v_lshlrev_b32_e32 v185, 16, v61
	v_lshlrev_b32_e32 v186, 16, v62
	v_lshlrev_b32_e32 v187, 16, v63
	v_and_b32_e32 v56, 0xffff0000, v60
	v_and_b32_e32 v57, 0xffff0000, v61
	v_and_b32_e32 v58, 0xffff0000, v62
	v_and_b32_e32 v59, 0xffff0000, v63
	v_mul_f32_e32 v56, v56, v56
	v_mul_f32_e32 v57, v57, v57
	v_mul_f32_e32 v58, v58, v58
	v_mul_f32_e32 v59, v59, v59
	v_fmac_f32_e32 v56, v184, v184
	v_fmac_f32_e32 v57, v185, v185
	v_fmac_f32_e32 v58, v186, v186
	v_fmac_f32_e32 v59, v187, v187
	v_add_f32_e32 v56, v56, v57
	v_add_f32_e32 v56, v56, v58
	v_add_f32_e32 v56, v56, v59
	s_waitcnt vmcnt(19)
	v_pk_add_f32 v[52:53], v[52:53], v[192:193]
	v_pk_add_f32 v[54:55], v[54:55], v[194:195]
	v_pk_add_f32 v[48:49], v[48:49], v[196:197]
	v_pk_add_f32 v[50:51], v[50:51], v[198:199]
	v_cvt_pk_bf16_f32 v52, v52, v53
	v_cvt_pk_bf16_f32 v53, v54, v55
	v_cvt_pk_bf16_f32 v54, v48, v49
	v_cvt_pk_bf16_f32 v55, v50, v51
	global_store_dwordx4 v151, v[52:55], s[74:75] offset:256
	v_lshlrev_b32_e32 v192, 16, v52
	v_lshlrev_b32_e32 v193, 16, v53
	v_lshlrev_b32_e32 v194, 16, v54
	v_lshlrev_b32_e32 v195, 16, v55
	v_and_b32_e32 v48, 0xffff0000, v52
	v_and_b32_e32 v49, 0xffff0000, v53
	v_and_b32_e32 v50, 0xffff0000, v54
	v_and_b32_e32 v51, 0xffff0000, v55
	v_mul_f32_e32 v48, v48, v48
	v_mul_f32_e32 v49, v49, v49
	v_mul_f32_e32 v50, v50, v50
	v_mul_f32_e32 v51, v51, v51
	v_fmac_f32_e32 v48, v192, v192
	v_fmac_f32_e32 v49, v193, v193
	v_fmac_f32_e32 v50, v194, v194
	v_fmac_f32_e32 v51, v195, v195
	v_add_f32_e32 v48, v48, v49
	v_add_f32_e32 v48, v48, v50
	v_add_f32_e32 v48, v48, v51
	v_add_f32_e32 v56, v56, v48
	v_add_u32_e32 v151, 0x8000, v151
	s_waitcnt vmcnt(16)
	v_pk_add_f32 v[44:45], v[44:45], v[200:201]
	v_pk_add_f32 v[46:47], v[46:47], v[202:203]
	v_pk_add_f32 v[40:41], v[40:41], v[204:205]
	v_pk_add_f32 v[42:43], v[42:43], v[206:207]
	v_cvt_pk_bf16_f32 v44, v44, v45
	v_cvt_pk_bf16_f32 v45, v46, v47
	v_cvt_pk_bf16_f32 v46, v40, v41
	v_cvt_pk_bf16_f32 v47, v42, v43
	global_store_dwordx4 v151, v[44:47], s[74:75]
	v_lshlrev_b32_e32 v200, 16, v44
	v_lshlrev_b32_e32 v201, 16, v45
	v_lshlrev_b32_e32 v202, 16, v46
	v_lshlrev_b32_e32 v203, 16, v47
	v_and_b32_e32 v40, 0xffff0000, v44
	v_and_b32_e32 v41, 0xffff0000, v45
	v_and_b32_e32 v42, 0xffff0000, v46
	v_and_b32_e32 v43, 0xffff0000, v47
	v_mul_f32_e32 v40, v40, v40
	v_mul_f32_e32 v41, v41, v41
	v_mul_f32_e32 v42, v42, v42
	v_mul_f32_e32 v43, v43, v43
	v_fmac_f32_e32 v40, v200, v200
	v_fmac_f32_e32 v41, v201, v201
	v_fmac_f32_e32 v42, v202, v202
	v_fmac_f32_e32 v43, v203, v203
	v_add_f32_e32 v40, v40, v41
	v_add_f32_e32 v40, v40, v42
	v_add_f32_e32 v40, v40, v43
	s_waitcnt vmcnt(15)
	v_pk_add_f32 v[36:37], v[36:37], v[208:209]
	v_pk_add_f32 v[38:39], v[38:39], v[210:211]
	v_pk_add_f32 v[32:33], v[32:33], v[212:213]
	v_pk_add_f32 v[34:35], v[34:35], v[214:215]
	v_cvt_pk_bf16_f32 v36, v36, v37
	v_cvt_pk_bf16_f32 v37, v38, v39
	v_cvt_pk_bf16_f32 v38, v32, v33
	v_cvt_pk_bf16_f32 v39, v34, v35
	global_store_dwordx4 v151, v[36:39], s[74:75] offset:256
	v_lshlrev_b32_e32 v208, 16, v36
	v_lshlrev_b32_e32 v209, 16, v37
	v_lshlrev_b32_e32 v210, 16, v38
	v_lshlrev_b32_e32 v211, 16, v39
	v_and_b32_e32 v32, 0xffff0000, v36
	v_and_b32_e32 v33, 0xffff0000, v37
	v_and_b32_e32 v34, 0xffff0000, v38
	v_and_b32_e32 v35, 0xffff0000, v39
	v_mul_f32_e32 v32, v32, v32
	v_mul_f32_e32 v33, v33, v33
	v_mul_f32_e32 v34, v34, v34
	v_mul_f32_e32 v35, v35, v35
	v_fmac_f32_e32 v32, v208, v208
	v_fmac_f32_e32 v33, v209, v209
	v_fmac_f32_e32 v34, v210, v210
	v_fmac_f32_e32 v35, v211, v211
	v_add_f32_e32 v32, v32, v33
	v_add_f32_e32 v32, v32, v34
	v_add_f32_e32 v32, v32, v35
	v_add_f32_e32 v40, v40, v32
	v_add_u32_e32 v151, 0x8000, v151
	s_waitcnt vmcnt(12)
	v_pk_add_f32 v[28:29], v[28:29], v[216:217]
	v_pk_add_f32 v[30:31], v[30:31], v[218:219]
	v_pk_add_f32 v[24:25], v[24:25], v[220:221]
	v_pk_add_f32 v[26:27], v[26:27], v[222:223]
	v_cvt_pk_bf16_f32 v28, v28, v29
	v_cvt_pk_bf16_f32 v29, v30, v31
	v_cvt_pk_bf16_f32 v30, v24, v25
	v_cvt_pk_bf16_f32 v31, v26, v27
	global_store_dwordx4 v151, v[28:31], s[74:75]
	v_lshlrev_b32_e32 v216, 16, v28
	v_lshlrev_b32_e32 v217, 16, v29
	v_lshlrev_b32_e32 v218, 16, v30
	v_lshlrev_b32_e32 v219, 16, v31
	v_and_b32_e32 v24, 0xffff0000, v28
	v_and_b32_e32 v25, 0xffff0000, v29
	v_and_b32_e32 v26, 0xffff0000, v30
	v_and_b32_e32 v27, 0xffff0000, v31
	v_mul_f32_e32 v24, v24, v24
	v_mul_f32_e32 v25, v25, v25
	v_mul_f32_e32 v26, v26, v26
	v_mul_f32_e32 v27, v27, v27
	v_fmac_f32_e32 v24, v216, v216
	v_fmac_f32_e32 v25, v217, v217
	v_fmac_f32_e32 v26, v218, v218
	v_fmac_f32_e32 v27, v219, v219
	v_add_f32_e32 v24, v24, v25
	v_add_f32_e32 v24, v24, v26
	v_add_f32_e32 v24, v24, v27
	s_waitcnt vmcnt(11)
	v_pk_add_f32 v[20:21], v[20:21], v[224:225]
	v_pk_add_f32 v[22:23], v[22:23], v[226:227]
	v_pk_add_f32 v[16:17], v[16:17], v[228:229]
	v_pk_add_f32 v[18:19], v[18:19], v[230:231]
	v_cvt_pk_bf16_f32 v20, v20, v21
	v_cvt_pk_bf16_f32 v21, v22, v23
	v_cvt_pk_bf16_f32 v22, v16, v17
	v_cvt_pk_bf16_f32 v23, v18, v19
	global_store_dwordx4 v151, v[20:23], s[74:75] offset:256
	v_lshlrev_b32_e32 v224, 16, v20
	v_lshlrev_b32_e32 v225, 16, v21
	v_lshlrev_b32_e32 v226, 16, v22
	v_lshlrev_b32_e32 v227, 16, v23
	v_and_b32_e32 v16, 0xffff0000, v20
	v_and_b32_e32 v17, 0xffff0000, v21
	v_and_b32_e32 v18, 0xffff0000, v22
	v_and_b32_e32 v19, 0xffff0000, v23
	v_mul_f32_e32 v16, v16, v16
	v_mul_f32_e32 v17, v17, v17
	v_mul_f32_e32 v18, v18, v18
	v_mul_f32_e32 v19, v19, v19
	v_fmac_f32_e32 v16, v224, v224
	v_fmac_f32_e32 v17, v225, v225
	v_fmac_f32_e32 v18, v226, v226
	v_fmac_f32_e32 v19, v227, v227
	v_add_f32_e32 v16, v16, v17
	v_add_f32_e32 v16, v16, v18
	v_add_f32_e32 v16, v16, v19
	v_add_f32_e32 v24, v24, v16
	v_add_u32_e32 v151, 0x8000, v151
	s_waitcnt vmcnt(8)
	v_pk_add_f32 v[12:13], v[12:13], v[162:163]
	v_pk_add_f32 v[14:15], v[14:15], v[164:165]
	v_pk_add_f32 v[8:9], v[8:9], v[166:167]
	v_pk_add_f32 v[10:11], v[10:11], v[168:169]
	v_cvt_pk_bf16_f32 v12, v12, v13
	v_cvt_pk_bf16_f32 v13, v14, v15
	v_cvt_pk_bf16_f32 v14, v8, v9
	v_cvt_pk_bf16_f32 v15, v10, v11
	global_store_dwordx4 v151, v[12:15], s[74:75]
	v_lshlrev_b32_e32 v162, 16, v12
	v_lshlrev_b32_e32 v163, 16, v13
	v_lshlrev_b32_e32 v164, 16, v14
	v_lshlrev_b32_e32 v165, 16, v15
	v_and_b32_e32 v8, 0xffff0000, v12
	v_and_b32_e32 v9, 0xffff0000, v13
	v_and_b32_e32 v10, 0xffff0000, v14
	v_and_b32_e32 v11, 0xffff0000, v15
	v_mul_f32_e32 v8, v8, v8
	v_mul_f32_e32 v9, v9, v9
	v_mul_f32_e32 v10, v10, v10
	v_mul_f32_e32 v11, v11, v11
	v_fmac_f32_e32 v8, v162, v162
	v_fmac_f32_e32 v9, v163, v163
	v_fmac_f32_e32 v10, v164, v164
	v_fmac_f32_e32 v11, v165, v165
	v_add_f32_e32 v8, v8, v9
	v_add_f32_e32 v8, v8, v10
	v_add_f32_e32 v8, v8, v11
	s_waitcnt vmcnt(7)
	v_pk_add_f32 v[4:5], v[4:5], v[170:171]
	v_pk_add_f32 v[6:7], v[6:7], v[172:173]
	v_pk_add_f32 v[0:1], v[0:1], v[152:153]
	v_pk_add_f32 v[2:3], v[2:3], v[154:155]
	v_cvt_pk_bf16_f32 v4, v4, v5
	v_cvt_pk_bf16_f32 v5, v6, v7
	v_cvt_pk_bf16_f32 v6, v0, v1
	v_cvt_pk_bf16_f32 v7, v2, v3
	global_store_dwordx4 v151, v[4:7], s[74:75] offset:256
	v_lshlrev_b32_e32 v170, 16, v4
	v_lshlrev_b32_e32 v171, 16, v5
	v_lshlrev_b32_e32 v172, 16, v6
	v_lshlrev_b32_e32 v173, 16, v7
	v_and_b32_e32 v0, 0xffff0000, v4
	v_and_b32_e32 v1, 0xffff0000, v5
	v_and_b32_e32 v2, 0xffff0000, v6
	v_and_b32_e32 v3, 0xffff0000, v7
	v_mul_f32_e32 v0, v0, v0
	v_mul_f32_e32 v1, v1, v1
	v_mul_f32_e32 v2, v2, v2
	v_mul_f32_e32 v3, v3, v3
	v_fmac_f32_e32 v0, v170, v170
	v_fmac_f32_e32 v1, v171, v171
	v_fmac_f32_e32 v2, v172, v172
	v_fmac_f32_e32 v3, v173, v173
	v_add_f32_e32 v0, v0, v1
	v_add_f32_e32 v0, v0, v2
	v_add_f32_e32 v0, v0, v3
	v_add_f32_e32 v8, v8, v0
	v_mov_b32_e32 v175, v122
	s_nop 1
	v_permlane16_swap_b32_e32 v175, v122
	v_add_f32_e32 v122, v175, v122
	v_mov_b32_e32 v175, v106
	s_nop 1
	v_permlane16_swap_b32_e32 v175, v106
	v_add_f32_e32 v106, v175, v106
	v_mov_b32_e32 v175, v90
	s_nop 1
	v_permlane16_swap_b32_e32 v175, v90
	v_add_f32_e32 v90, v175, v90
	v_mov_b32_e32 v175, v74
	s_nop 1
	v_permlane16_swap_b32_e32 v175, v74
	v_add_f32_e32 v74, v175, v74
	v_mov_b32_e32 v175, v56
	s_nop 1
	v_permlane16_swap_b32_e32 v175, v56
	v_add_f32_e32 v56, v175, v56
	v_mov_b32_e32 v175, v40
	s_nop 1
	v_permlane16_swap_b32_e32 v175, v40
	v_add_f32_e32 v40, v175, v40
	v_mov_b32_e32 v175, v24
	s_nop 1
	v_permlane16_swap_b32_e32 v175, v24
	v_add_f32_e32 v24, v175, v24
	v_mov_b32_e32 v175, v8
	s_nop 1
	v_permlane16_swap_b32_e32 v175, v8
	v_add_f32_e32 v8, v175, v8
	v_mov_b32_e32 v175, v122
	s_nop 1
	v_permlane32_swap_b32_e32 v175, v122
	v_add_f32_e32 v122, v175, v122
	v_mov_b32_e32 v175, v106
	s_nop 1
	v_permlane32_swap_b32_e32 v175, v106
	v_add_f32_e32 v106, v175, v106
	v_mov_b32_e32 v175, v90
	s_nop 1
	v_permlane32_swap_b32_e32 v175, v90
	v_add_f32_e32 v90, v175, v90
	v_mov_b32_e32 v175, v74
	s_nop 1
	v_permlane32_swap_b32_e32 v175, v74
	v_add_f32_e32 v74, v175, v74
	v_mov_b32_e32 v175, v56
	s_nop 1
	v_permlane32_swap_b32_e32 v175, v56
	v_add_f32_e32 v56, v175, v56
	v_mov_b32_e32 v175, v40
	s_nop 1
	v_permlane32_swap_b32_e32 v175, v40
	v_add_f32_e32 v40, v175, v40
	v_mov_b32_e32 v175, v24
	s_nop 1
	v_permlane32_swap_b32_e32 v175, v24
	v_add_f32_e32 v24, v175, v24
	v_mov_b32_e32 v175, v8
	s_nop 1
	v_permlane32_swap_b32_e32 v175, v8
	v_add_f32_e32 v8, v175, v8
	s_add_u32 s74, s28, s54
	s_addc_u32 s75, s29, 0
	s_and_saveexec_b64 s[4:5], s[38:39]
	s_nop 1
	global_store_dword v149, v122, s[74:75]
	v_add_u32_e32 v149, 0x400, v149
	global_store_dword v149, v106, s[74:75]
	v_add_u32_e32 v149, 0x400, v149
	global_store_dword v149, v90, s[74:75]
	v_add_u32_e32 v149, 0x400, v149
	global_store_dword v149, v74, s[74:75]
	v_add_u32_e32 v149, 0x1400, v149
	global_store_dword v149, v56, s[74:75]
	v_add_u32_e32 v149, 0x400, v149
	global_store_dword v149, v40, s[74:75]
	v_add_u32_e32 v149, 0x400, v149
	global_store_dword v149, v24, s[74:75]
	v_add_u32_e32 v149, 0x400, v149
	global_store_dword v149, v8, s[74:75]
	s_or_b64 exec, exec, s[4:5]
	s_mov_b32 s54, s55
	s_mov_b32 s55, 0
	s_lshl_b32 s76, s20, 2
	v_readlane_b32 s74, v255, 32
	v_readlane_b32 s75, v255, 33
	s_movk_i32 s78, 0xf800
	v_readlane_b32 s70, v255, 26
	v_readlane_b32 s71, v255, 27
	s_branch .Lout_done
	v_lshl_add_u32 v150, s29, 8, v161
	s_lshl_b32 s4, s28, 8
	s_ashr_i32 s5, s4, 31
	v_ashrrev_i32_e32 v151, 31, v150
	v_mov_b32_e32 v149, s5
	v_or_b32_e32 v148, s4, v142
	v_lshlrev_b64 v[152:153], 10, v[150:151]
	v_lshl_add_u64 v[156:157], v[152:153], 0, v[148:149]
	v_lshl_add_u64 v[166:167], v[156:157], 2, s[36:37]
	global_load_dwordx4 v[152:155], v[166:167], off
	global_load_dwordx4 v[162:165], v[166:167], off offset:16
	v_lshl_add_u64 v[156:157], v[156:157], 1, s[30:31]
	s_lshl_b32 s54, s28, 2
	s_ashr_i32 s55, s54, 31
	s_waitcnt vmcnt(0)
	v_pk_add_f32 v[126:127], v[126:127], v[152:153]
	v_pk_add_f32 v[128:129], v[128:129], v[154:155]
	v_pk_add_f32 v[152:153], v[124:125], v[164:165]
	v_pk_add_f32 v[122:123], v[122:123], v[162:163]
	v_cvt_pk_bf16_f32 v124, v126, v127
	v_cvt_pk_bf16_f32 v125, v128, v129
	s_nop 0
	v_cvt_pk_bf16_f32 v126, v122, v123
	v_cvt_pk_bf16_f32 v127, v152, v153
	global_store_dwordx4 v[156:157], v[124:127], off
	global_load_dwordx4 v[152:155], v[166:167], off offset:512
	global_load_dwordx4 v[162:165], v[166:167], off offset:528
	v_lshlrev_b32_e32 v128, 16, v124
	v_and_b32_e32 v124, 0xffff0000, v124
	v_lshlrev_b32_e32 v129, 16, v125
	v_and_b32_e32 v125, 0xffff0000, v125
	v_lshlrev_b32_e32 v138, 16, v126
	v_and_b32_e32 v126, 0xffff0000, v126
	v_mul_f32_e32 v124, v124, v124
	v_mul_f32_e32 v125, v125, v125
	v_mul_f32_e32 v126, v126, v126
	v_fmac_f32_e32 v124, v128, v128
	v_fmac_f32_e32 v125, v129, v129
	v_lshlrev_b32_e32 v139, 16, v127
	v_and_b32_e32 v127, 0xffff0000, v127
	v_fmac_f32_e32 v126, v138, v138
	v_add_f32_e32 v124, v124, v125
	v_mul_f32_e32 v127, v127, v127
	v_add_f32_e32 v124, v124, v126
	v_and_b32_e32 v123, 64, v178
	v_fmac_f32_e32 v127, v139, v139
	v_xor_b32_e32 v122, 16, v178
	v_add_u32_e32 v123, 64, v123
	v_add_f32_e32 v124, v124, v127
	v_cmp_lt_i32_e32 vcc, v122, v123
	s_waitcnt vmcnt(1)
	v_pk_add_f32 v[120:121], v[120:121], v[154:155]
	v_pk_add_f32 v[118:119], v[118:119], v[152:153]
	s_waitcnt vmcnt(0)
	v_pk_add_f32 v[116:117], v[116:117], v[164:165]
	v_pk_add_f32 v[114:115], v[114:115], v[162:163]
	v_cvt_pk_bf16_f32 v118, v118, v119
	v_cvt_pk_bf16_f32 v119, v120, v121
	v_cndmask_b32_e32 v122, v178, v122, vcc
	v_cvt_pk_bf16_f32 v120, v114, v115
	v_cvt_pk_bf16_f32 v121, v116, v117
	v_and_b32_e32 v115, 0xffff0000, v118
	v_and_b32_e32 v117, 0xffff0000, v119
	v_lshlrev_b32_e32 v114, 16, v118
	v_lshlrev_b32_e32 v116, 16, v119
	v_and_b32_e32 v126, 0xffff0000, v120
	v_mul_f32_e32 v115, v115, v115
	v_mul_f32_e32 v117, v117, v117
	v_lshlrev_b32_e32 v125, 16, v120
	v_and_b32_e32 v128, 0xffff0000, v121
	v_mul_f32_e32 v126, v126, v126
	v_fmac_f32_e32 v115, v114, v114
	v_fmac_f32_e32 v117, v116, v116
	v_lshlrev_b32_e32 v127, 16, v121
	v_mul_f32_e32 v128, v128, v128
	v_fmac_f32_e32 v126, v125, v125
	v_add_f32_e32 v114, v115, v117
	v_fmac_f32_e32 v128, v127, v127
	v_add_f32_e32 v114, v114, v126
	v_add_f32_e32 v114, v114, v128
	v_lshlrev_b32_e32 v122, 2, v122
	v_add_f32_e32 v114, v124, v114
	ds_bpermute_b32 v115, v122, v114
	v_xor_b32_e32 v116, 32, v178
	v_cmp_lt_i32_e32 vcc, v116, v123
	global_store_dwordx4 v[156:157], v[118:121], off offset:256
	s_waitcnt lgkmcnt(0)
	v_add_f32_e32 v114, v114, v115
	v_cndmask_b32_e32 v116, v178, v116, vcc
	v_lshlrev_b32_e32 v116, 2, v116
	ds_bpermute_b32 v115, v116, v114
	s_and_saveexec_b64 s[4:5], s[38:39]
	s_movk_i32 s78, 0xf800
	s_cbranch_execz .LBB0_188
	v_readlane_b32 s28, v250, 23
	v_lshlrev_b64 v[118:119], 6, v[150:151]
	v_readlane_b32 s29, v250, 24
	s_lshl_b32 s76, s20, 2
	s_waitcnt lgkmcnt(0)
	v_add_f32_e32 v114, v114, v115
	v_lshl_add_u64 v[118:119], s[28:29], 0, v[118:119]
	v_lshl_add_u64 v[118:119], s[54:55], 2, v[118:119]
	v_lshl_add_u64 v[118:119], v[118:119], 0, s[76:77]
	global_store_dword v[118:119], v114, off
